# SSD chunk-output phase: z rows and output-norm gain fragments of a 64-row half requested together at the start of the gating code; gain fragments no longer re-loaded behind every store
# speedup vs baseline: 1.0402x; 1.0014x over previous
.LBB0_848:
	s_or_b64 exec, exec, s[0:1]
	s_waitcnt lgkmcnt(0)
	s_barrier
	v_lshl_add_u32 v35, v243, 2, s4
	v_add_u32_e32 v35, 0xa800, v35
	v_mov_b64_e32 v[42:43], s[64:65]
	s_mov_b32 s0, 0x358637bd
	ds_read2_b32 v[86:87], v35 offset1:16
	ds_read2_b32 v[88:89], v35 offset0:64 offset1:80
	ds_read2_b32 v[90:91], v35 offset0:128 offset1:144
	ds_read2_b32 v[92:93], v35 offset0:192 offset1:208
	v_lshlrev_b64 v[74:75], 1, v[122:123]
	v_mov_b64_e32 v[84:85], s[0:1]
	v_mad_i64_i32 v[54:55], s[0:1], v54, s77, v[42:43]
	v_lshlrev_b32_e32 v144, 1, v118
	v_lshl_add_u64 v[54:55], v[54:55], 0, v[74:75]
	v_lshl_add_u64 v[94:95], v[54:55], 0, v[144:145]
	s_waitcnt lgkmcnt(3)
	v_mov_b32_e32 v54, v87
	v_mov_b32_e32 v55, v86
	s_waitcnt lgkmcnt(2)
	v_mov_b32_e32 v86, v89
	v_mov_b32_e32 v87, v88
	s_waitcnt lgkmcnt(1)
	v_mov_b32_e32 v88, v91
	v_mov_b32_e32 v89, v90
	v_pk_add_f32 v[54:55], v[54:55], v[86:87]
	s_waitcnt lgkmcnt(0)
	v_mov_b32_e32 v90, v93
	v_mov_b32_e32 v91, v92
	v_pk_add_f32 v[54:55], v[54:55], v[88:89]
	s_mov_b32 s12, 0x3b800000
	v_pk_add_f32 v[54:55], v[54:55], v[90:91]
	s_mov_b32 s8, 0x800000
	v_pk_fma_f32 v[86:87], v[54:55], s[12:13], v[84:85] op_sel_hi:[1,0,0]
	s_mov_b64 s[10:11], 0xc200400
	v_mul_f32_e32 v54, 0x4b800000, v87
	v_cmp_gt_f32_e32 vcc, s8, v87
	s_mov_b32 s9, 1
	s_nop 0
	v_cndmask_b32_e32 v54, v87, v54, vcc
	v_rsq_f32_e32 v67, v54
	v_add_co_u32_e64 v54, s[0:1], s68, v94
	v_mul_f32_e32 v73, 0x45800000, v67
	v_cndmask_b32_e32 v88, v67, v73, vcc
	v_pk_mul_f32 v[48:49], v[48:49], v[88:89] op_sel_hi:[1,0]
	v_pk_mul_f32 v[50:51], v[50:51], v[88:89] op_sel_hi:[1,0]
	v_pk_mul_f32 v[52:53], v[52:53], v[88:89] op_sel_hi:[1,0]
	v_pk_mul_f32 v[56:57], v[56:57], v[88:89] op_sel_hi:[1,0]
	v_addc_co_u32_e64 v55, s[0:1], 0, v95, s[0:1]
	v_pk_mul_f32 v[58:59], v[58:59], v[88:89] op_sel_hi:[1,0]
	v_pk_mul_f32 v[60:61], v[60:61], v[88:89] op_sel_hi:[1,0]
	v_pk_mul_f32 v[62:63], v[62:63], v[88:89] op_sel_hi:[1,0]
	v_pk_mul_f32 v[64:65], v[64:65], v[88:89] op_sel_hi:[1,0]
	v_cmp_gt_f32_e32 vcc, s8, v86
	s_nop 1
	v_mov_b32_e32 v76, v182
	v_mov_b32_e32 v77, v183
	v_mov_b32_e32 v78, v184
	v_mov_b32_e32 v79, v185
	v_pk_mul_f32 v[48:49], v[76:77], v[48:49]
	v_pk_mul_f32 v[50:51], v[78:79], v[50:51]
	s_nop 1
	v_mov_b32_e32 v80, v186
	v_mov_b32_e32 v81, v187
	v_mov_b32_e32 v82, v188
	v_mov_b32_e32 v83, v189
	v_pk_mul_f32 v[52:53], v[80:81], v[52:53]
	v_pk_mul_f32 v[56:57], v[82:83], v[56:57]
	v_cvt_pk_bf16_f32 v48, v48, v49
	v_cvt_pk_bf16_f32 v49, v50, v51
	v_cvt_pk_bf16_f32 v50, v52, v53
	v_cvt_pk_bf16_f32 v51, v56, v57
	global_store_dwordx4 v[54:55], v[48:51], off offset:1024
	s_nop 0
	v_lshl_add_u64 v[56:57], v[94:95], 0, s[10:11]
	s_nop 1
	v_mov_b32_e32 v48, v190
	v_mov_b32_e32 v49, v191
	v_mov_b32_e32 v50, v192
	v_mov_b32_e32 v51, v193
	v_pk_mul_f32 v[48:49], v[58:59], v[48:49]
	v_pk_mul_f32 v[50:51], v[60:61], v[50:51]
	s_nop 1
	v_mov_b32_e32 v52, v194
	v_mov_b32_e32 v53, v195
	v_mov_b32_e32 v54, v196
	v_mov_b32_e32 v55, v197
	v_pk_mul_f32 v[52:53], v[62:63], v[52:53]
	v_pk_mul_f32 v[54:55], v[64:65], v[54:55]
	v_cvt_pk_bf16_f32 v48, v48, v49
	v_cvt_pk_bf16_f32 v49, v50, v51
	v_cvt_pk_bf16_f32 v50, v52, v53
	v_cvt_pk_bf16_f32 v51, v54, v55
	global_store_dwordx4 v[56:57], v[48:51], off offset:64
	s_nop 0
	v_mul_f32_e32 v58, 0x4b800000, v86
	v_cndmask_b32_e32 v58, v86, v58, vcc
	v_rsq_f32_e32 v60, v58
	v_mad_i64_i32 v[56:57], s[0:1], v66, s77, v[42:43]
	v_lshl_add_u64 v[56:57], v[56:57], 0, v[74:75]
	v_mul_f32_e32 v61, 0x45800000, v60
	v_cndmask_b32_e32 v60, v60, v61, vcc
	v_lshl_add_u64 v[56:57], v[56:57], 0, v[144:145]
	v_pk_mul_f32 v[36:37], v[36:37], v[60:61] op_sel_hi:[1,0]
	v_pk_mul_f32 v[38:39], v[38:39], v[60:61] op_sel_hi:[1,0]
	v_pk_mul_f32 v[44:45], v[44:45], v[60:61] op_sel_hi:[1,0]
	v_pk_mul_f32 v[46:47], v[46:47], v[60:61] op_sel_hi:[1,0]
	v_add_co_u32_e64 v58, s[0:1], s68, v56
	v_pk_mul_f32 v[20:21], v[20:21], v[60:61] op_sel_hi:[1,0]
	s_nop 0
	v_addc_co_u32_e64 v59, s[0:1], 0, v57, s[0:1]
	v_pk_mul_f32 v[22:23], v[22:23], v[60:61] op_sel_hi:[1,0]
	v_pk_mul_f32 v[32:33], v[32:33], v[60:61] op_sel_hi:[1,0]
	s_nop 1
	v_mov_b32_e32 v48, v182
	v_mov_b32_e32 v49, v183
	v_mov_b32_e32 v50, v184
	v_mov_b32_e32 v51, v185
	v_pk_mul_f32 v[36:37], v[48:49], v[36:37]
	v_pk_mul_f32 v[38:39], v[50:51], v[38:39]
	s_nop 1
	v_mov_b32_e32 v52, v186
	v_mov_b32_e32 v53, v187
	v_mov_b32_e32 v54, v188
	v_mov_b32_e32 v55, v189
	v_pk_mul_f32 v[44:45], v[52:53], v[44:45]
	v_pk_mul_f32 v[46:47], v[54:55], v[46:47]
	v_cvt_pk_bf16_f32 v36, v36, v37
	v_cvt_pk_bf16_f32 v37, v38, v39
	v_cvt_pk_bf16_f32 v38, v44, v45
	v_cvt_pk_bf16_f32 v39, v46, v47
	global_store_dwordx4 v[58:59], v[36:39], off offset:1024
	s_nop 0
	v_pk_mul_f32 v[50:51], v[68:69], v[60:61] op_sel_hi:[1,0]
	v_lshl_add_u64 v[48:49], v[56:57], 0, s[10:11]
	s_nop 1
	v_mov_b32_e32 v36, v190
	v_mov_b32_e32 v37, v191
	v_mov_b32_e32 v38, v192
	v_mov_b32_e32 v39, v193
	v_pk_mul_f32 v[20:21], v[20:21], v[36:37]
	v_pk_mul_f32 v[22:23], v[22:23], v[38:39]
	s_nop 1
	v_mov_b32_e32 v44, v194
	v_mov_b32_e32 v45, v195
	v_mov_b32_e32 v46, v196
	v_mov_b32_e32 v47, v197
	v_pk_mul_f32 v[32:33], v[32:33], v[44:45]
	v_pk_mul_f32 v[36:37], v[50:51], v[46:47]
	v_cvt_pk_bf16_f32 v20, v20, v21
	v_cvt_pk_bf16_f32 v21, v22, v23
	v_cvt_pk_bf16_f32 v22, v32, v33
	v_cvt_pk_bf16_f32 v23, v36, v37
	global_store_dwordx4 v[48:49], v[20:23], off offset:64
	s_nop 0
	ds_read2_b32 v[32:33], v35 offset0:32 offset1:48
	ds_read2_b32 v[44:45], v35 offset0:96 offset1:112
	ds_read2_b32 v[46:47], v35 offset0:160 offset1:176
	ds_read2_b32 v[48:49], v35 offset0:224 offset1:240
	v_mad_i64_i32 v[34:35], s[0:1], v34, s77, v[42:43]
	s_waitcnt lgkmcnt(3)
	v_mov_b32_e32 v50, v33
	v_mov_b32_e32 v51, v32
	s_waitcnt lgkmcnt(2)
	v_mov_b32_e32 v32, v45
	v_mov_b32_e32 v33, v44
	s_waitcnt lgkmcnt(1)
	v_mov_b32_e32 v44, v47
	v_mov_b32_e32 v45, v46
	v_pk_add_f32 v[32:33], v[50:51], v[32:33]
	s_waitcnt lgkmcnt(0)
	v_mov_b32_e32 v46, v49
	v_mov_b32_e32 v47, v48
	v_pk_add_f32 v[32:33], v[32:33], v[44:45]
	v_lshl_add_u64 v[34:35], v[34:35], 0, v[74:75]
	v_pk_add_f32 v[32:33], v[32:33], v[46:47]
	v_lshl_add_u64 v[34:35], v[34:35], 0, v[144:145]
	v_pk_fma_f32 v[32:33], v[32:33], s[12:13], v[84:85] op_sel_hi:[1,0,0]
	s_nop 0
	v_mul_f32_e32 v44, 0x4b800000, v33
	v_cmp_gt_f32_e32 vcc, s8, v33
	s_nop 1
	v_cndmask_b32_e32 v33, v33, v44, vcc
	v_rsq_f32_e32 v33, v33
	v_add_co_u32_e64 v44, s[0:1], s68, v34
	v_mul_f32_e32 v46, 0x45800000, v33
	v_cndmask_b32_e32 v46, v33, v46, vcc
	v_pk_mul_f32 v[8:9], v[8:9], v[46:47] op_sel_hi:[1,0]
	v_pk_mul_f32 v[10:11], v[10:11], v[46:47] op_sel_hi:[1,0]
	v_pk_mul_f32 v[12:13], v[12:13], v[46:47] op_sel_hi:[1,0]
	v_pk_mul_f32 v[14:15], v[14:15], v[46:47] op_sel_hi:[1,0]
	v_addc_co_u32_e64 v45, s[0:1], 0, v35, s[0:1]
	v_pk_mul_f32 v[0:1], v[0:1], v[46:47] op_sel_hi:[1,0]
	v_pk_mul_f32 v[2:3], v[2:3], v[46:47] op_sel_hi:[1,0]
	v_pk_mul_f32 v[4:5], v[4:5], v[46:47] op_sel_hi:[1,0]
	v_cmp_gt_f32_e32 vcc, s8, v32
	s_nop 1
	v_mov_b32_e32 v20, v182
	v_mov_b32_e32 v21, v183
	v_mov_b32_e32 v22, v184
	v_mov_b32_e32 v23, v185
	v_pk_mul_f32 v[8:9], v[20:21], v[8:9]
	v_pk_mul_f32 v[10:11], v[22:23], v[10:11]
	s_nop 1
	v_mov_b32_e32 v36, v186
	v_mov_b32_e32 v37, v187
	v_mov_b32_e32 v38, v188
	v_mov_b32_e32 v39, v189
	v_pk_mul_f32 v[12:13], v[36:37], v[12:13]
	v_pk_mul_f32 v[14:15], v[38:39], v[14:15]
	v_cvt_pk_bf16_f32 v8, v8, v9
	v_cvt_pk_bf16_f32 v9, v10, v11
	v_cvt_pk_bf16_f32 v10, v12, v13
	v_cvt_pk_bf16_f32 v11, v14, v15
	global_store_dwordx4 v[44:45], v[8:11], off offset:1024
	s_nop 0
	v_pk_mul_f32 v[22:23], v[70:71], v[46:47] op_sel_hi:[1,0]
	v_lshl_add_u64 v[20:21], v[34:35], 0, s[10:11]
	s_nop 1
	v_mov_b32_e32 v8, v190
	v_mov_b32_e32 v9, v191
	v_mov_b32_e32 v10, v192
	v_mov_b32_e32 v11, v193
	v_pk_mul_f32 v[0:1], v[0:1], v[8:9]
	v_pk_mul_f32 v[2:3], v[2:3], v[10:11]
	s_nop 1
	v_mov_b32_e32 v12, v194
	v_mov_b32_e32 v13, v195
	v_mov_b32_e32 v14, v196
	v_mov_b32_e32 v15, v197
	v_pk_mul_f32 v[4:5], v[4:5], v[12:13]
	v_pk_mul_f32 v[8:9], v[22:23], v[14:15]
	v_cvt_pk_bf16_f32 v0, v0, v1
	v_cvt_pk_bf16_f32 v1, v2, v3
	v_cvt_pk_bf16_f32 v2, v4, v5
	v_cvt_pk_bf16_f32 v3, v8, v9
	global_store_dwordx4 v[20:21], v[0:3], off offset:64
	s_nop 0
	v_mad_i64_i32 v[4:5], s[0:1], v72, s77, v[42:43]
	v_lshl_add_u64 v[4:5], v[4:5], 0, v[74:75]
	v_lshl_add_u64 v[12:13], v[4:5], 0, v[144:145]
	v_mul_f32_e32 v4, 0x4b800000, v32
	v_cndmask_b32_e32 v4, v32, v4, vcc
	v_rsq_f32_e32 v14, v4
	v_add_co_u32_e64 v4, s[0:1], s68, v12
	v_mul_f32_e32 v15, 0x45800000, v14
	v_cndmask_b32_e32 v14, v14, v15, vcc
	v_pk_mul_f32 v[6:7], v[6:7], v[14:15] op_sel_hi:[1,0]
	v_pk_mul_f32 v[20:21], v[28:29], v[14:15] op_sel_hi:[1,0]
	v_pk_mul_f32 v[22:23], v[30:31], v[14:15] op_sel_hi:[1,0]
	v_pk_mul_f32 v[28:29], v[40:41], v[14:15] op_sel_hi:[1,0]
	v_addc_co_u32_e64 v5, s[0:1], 0, v13, s[0:1]
	s_andn2_b64 vcc, exec, s[2:3]
	s_mov_b64 s[0:1], 0
	s_nop 1
	v_mov_b32_e32 v0, v182
	v_mov_b32_e32 v1, v183
	v_mov_b32_e32 v2, v184
	v_mov_b32_e32 v3, v185
	v_pk_mul_f32 v[0:1], v[0:1], v[6:7]
	v_pk_mul_f32 v[2:3], v[2:3], v[20:21]
	s_nop 1
	v_mov_b32_e32 v8, v186
	v_mov_b32_e32 v9, v187
	v_mov_b32_e32 v10, v188
	v_mov_b32_e32 v11, v189
	v_pk_mul_f32 v[6:7], v[8:9], v[22:23]
	v_pk_mul_f32 v[8:9], v[10:11], v[28:29]
	v_cvt_pk_bf16_f32 v0, v0, v1
	v_cvt_pk_bf16_f32 v1, v2, v3
	v_cvt_pk_bf16_f32 v2, v6, v7
	v_cvt_pk_bf16_f32 v3, v8, v9
	global_store_dwordx4 v[4:5], v[0:3], off offset:1024
	s_nop 0
	v_lshl_add_u64 v[8:9], v[12:13], 0, s[10:11]
	v_pk_mul_f32 v[10:11], v[16:17], v[14:15] op_sel_hi:[1,0]
	v_pk_mul_f32 v[12:13], v[18:19], v[14:15] op_sel_hi:[1,0]
	v_pk_mul_f32 v[16:17], v[24:25], v[14:15] op_sel_hi:[1,0]
	v_pk_mul_f32 v[14:15], v[26:27], v[14:15] op_sel_hi:[1,0]
	s_nop 1
	v_mov_b32_e32 v0, v190
	v_mov_b32_e32 v1, v191
	v_mov_b32_e32 v2, v192
	v_mov_b32_e32 v3, v193
	v_pk_mul_f32 v[0:1], v[10:11], v[0:1]
	v_pk_mul_f32 v[2:3], v[12:13], v[2:3]
	s_nop 1
	v_mov_b32_e32 v4, v194
	v_mov_b32_e32 v5, v195
	v_mov_b32_e32 v6, v196
	v_mov_b32_e32 v7, v197
	v_pk_mul_f32 v[4:5], v[16:17], v[4:5]
	v_pk_mul_f32 v[6:7], v[14:15], v[6:7]
	v_cvt_pk_bf16_f32 v0, v0, v1
	v_cvt_pk_bf16_f32 v1, v2, v3
	v_cvt_pk_bf16_f32 v2, v4, v5
	v_cvt_pk_bf16_f32 v3, v6, v7
	global_store_dwordx4 v[8:9], v[0:3], off offset:64
	s_barrier
	s_cbranch_vccz .LBB0_844

.LBB0_852:
	ds_read_b128 v[200:203], v250
	ds_read_b128 v[80:83], v250 offset:16
	ds_read_b128 v[204:207], v250 offset:512
	ds_read_b128 v[84:87], v250 offset:528
	ds_read_b128 v[98:101], v250 offset:1024
	ds_read_b128 v[102:105], v250 offset:1536
	ds_read_b128 v[90:93], v240
	ds_read_b128 v[182:185], v240 offset:8704
	s_waitcnt lgkmcnt(7)
	v_sub_f32_e32 v94, v152, v201
	v_exp_f32_e32 v94, v94
	v_add_u32_e32 v198, s9, v118
	s_waitcnt lgkmcnt(1)
	v_lshlrev_b32_e32 v88, 16, v90
	v_and_b32_e32 v89, 0xffff0000, v90
	v_lshlrev_b32_e32 v212, 16, v91
	v_and_b32_e32 v213, 0xffff0000, v91
	v_lshlrev_b32_e32 v90, 16, v92
	v_and_b32_e32 v91, 0xffff0000, v92
	v_sub_f32_e32 v92, v152, v200
	v_exp_f32_e32 v92, v92
	v_cmp_gt_u32_e32 vcc, v150, v198
	v_mul_f32_e32 v94, v94, v99
	v_lshlrev_b32_e32 v106, 16, v93
	v_and_b32_e32 v107, 0xffff0000, v93
	v_mul_f32_e32 v93, v92, v98
	v_cndmask_b32_e32 v95, 0, v94, vcc
	v_cmp_le_u32_e32 vcc, v198, v150
	v_sub_f32_e32 v92, v154, v204
	v_exp_f32_e32 v92, v92
	v_cndmask_b32_e32 v94, 0, v93, vcc
	v_sub_f32_e32 v93, v154, v205
	v_exp_f32_e32 v93, v93
	v_add_u32_e32 v199, 1, v198
	v_cmp_ge_u32_e32 vcc, v199, v163
	v_cmp_eq_u32_e64 s[0:1], v198, v150
	v_pk_mul_f32 v[92:93], v[92:93], v[102:103]
	ds_read_b128 v[208:211], v240 offset:13056
	v_cndmask_b32_e32 v93, 0, v93, vcc
	v_cmp_ge_u32_e32 vcc, v198, v150
	s_waitcnt lgkmcnt(1)
	v_lshlrev_b32_e32 v232, 16, v183
	v_and_b32_e32 v233, 0xffff0000, v183
	v_cndmask_b32_e32 v92, 0, v92, vcc
	v_cmp_eq_u32_e32 vcc, v199, v163
	v_pk_add_f32 v[92:93], v[94:95], v[92:93]
	v_cndmask_b32_e64 v94, 0, v120, s[0:1]
	v_cndmask_b32_e32 v95, 0, v119, vcc
	v_pk_fma_f32 v[88:89], v[92:93], v[88:89], v[94:95]
	ds_read_b128 v[94:97], v240 offset:4352
	v_sub_f32_e32 v92, v152, v202
	v_exp_f32_e32 v214, v92
	v_sub_f32_e32 v92, v154, v206
	v_exp_f32_e32 v216, v92
	v_sub_f32_e32 v92, v152, v203
	v_exp_f32_e32 v215, v92
	v_sub_f32_e32 v92, v154, v207
	v_exp_f32_e32 v217, v92
	v_sub_f32_e32 v92, v152, v80
	s_waitcnt lgkmcnt(0)
	v_lshlrev_b32_e32 v108, 16, v97
	v_and_b32_e32 v109, 0xffff0000, v97
	v_sub_f32_e32 v97, v153, v201
	v_exp_f32_e32 v180, v92
	v_sub_f32_e32 v92, v154, v84
	v_cvt_pk_bf16_f32 v88, v88, v89
	v_sub_f32_e32 v89, v153, v200
	v_exp_f32_e32 v97, v97
	v_exp_f32_e32 v176, v92
	v_sub_f32_e32 v92, v152, v81
	v_exp_f32_e32 v89, v89
	v_exp_f32_e32 v181, v92
	v_sub_f32_e32 v92, v154, v85
	v_exp_f32_e32 v177, v92
	v_sub_f32_e32 v92, v152, v82
	v_exp_f32_e32 v112, v92
	v_sub_f32_e32 v92, v154, v86
	v_cmp_gt_u32_e32 vcc, v144, v198
	v_mul_f32_e32 v97, v97, v99
	v_exp_f32_e32 v110, v92
	v_sub_f32_e32 v92, v152, v83
	v_mul_f32_e32 v89, v89, v98
	v_cndmask_b32_e32 v171, 0, v97, vcc
	v_cmp_le_u32_e32 vcc, v198, v144
	v_exp_f32_e32 v113, v92
	v_sub_f32_e32 v92, v154, v87
	v_cndmask_b32_e32 v170, 0, v89, vcc
	v_sub_f32_e32 v89, v155, v205
	v_exp_f32_e32 v111, v92
	v_lshlrev_b32_e32 v92, 16, v94
	v_and_b32_e32 v93, 0xffff0000, v94
	v_lshlrev_b32_e32 v218, 16, v95
	v_and_b32_e32 v219, 0xffff0000, v95
	v_lshlrev_b32_e32 v94, 16, v96
	v_and_b32_e32 v95, 0xffff0000, v96
	v_sub_f32_e32 v96, v155, v204
	v_exp_f32_e32 v97, v89
	v_sub_f32_e32 v89, v153, v202
	v_exp_f32_e32 v96, v96
	v_exp_f32_e32 v220, v89
	v_sub_f32_e32 v89, v155, v206
	v_exp_f32_e32 v222, v89
	v_sub_f32_e32 v89, v153, v203
	v_exp_f32_e32 v221, v89
	v_sub_f32_e32 v89, v155, v207
	v_exp_f32_e32 v223, v89
	v_sub_f32_e32 v89, v153, v80
	v_pk_mul_f32 v[96:97], v[96:97], v[102:103]
	v_cmp_ge_u32_e32 vcc, v199, v161
	v_exp_f32_e32 v190, v89
	v_sub_f32_e32 v89, v155, v84
	v_cndmask_b32_e32 v97, 0, v97, vcc
	v_cmp_ge_u32_e32 vcc, v198, v144
	v_exp_f32_e32 v188, v89
	v_sub_f32_e32 v89, v153, v81
	v_cndmask_b32_e32 v96, 0, v96, vcc
	v_cmp_eq_u32_e32 vcc, v199, v161
	v_cmp_eq_u32_e64 s[0:1], v198, v144
	v_exp_f32_e32 v191, v89
	v_sub_f32_e32 v89, v155, v85
	v_pk_add_f32 v[96:97], v[170:171], v[96:97]
	v_cndmask_b32_e64 v170, 0, v120, s[0:1]
	v_cndmask_b32_e32 v171, 0, v119, vcc
	v_exp_f32_e32 v189, v89
	v_sub_f32_e32 v89, v153, v82
	v_pk_fma_f32 v[92:93], v[96:97], v[92:93], v[170:171]
	v_exp_f32_e32 v174, v89
	v_sub_f32_e32 v89, v155, v86
	v_exp_f32_e32 v172, v89
	v_sub_f32_e32 v89, v153, v83
	v_cvt_pk_bf16_f32 v92, v92, v93
	v_sub_f32_e32 v93, v158, v204
	v_exp_f32_e32 v175, v89
	v_sub_f32_e32 v89, v155, v87
	v_exp_f32_e32 v178, v93
	v_sub_f32_e32 v93, v156, v201
	v_exp_f32_e32 v173, v89
	v_sub_f32_e32 v89, v156, v200
	v_exp_f32_e32 v93, v93
	v_exp_f32_e32 v89, v89
	v_cmp_gt_u32_e32 vcc, v160, v198
	v_lshlrev_b32_e32 v96, 16, v182
	v_mul_f32_e32 v93, v93, v99
	v_mul_f32_e32 v89, v89, v98
	v_cndmask_b32_e32 v183, 0, v93, vcc
	v_cmp_le_u32_e32 vcc, v198, v160
	v_and_b32_e32 v97, 0xffff0000, v182
	v_lshlrev_b32_e32 v186, 16, v184
	v_cndmask_b32_e32 v182, 0, v89, vcc
	v_sub_f32_e32 v89, v158, v205
	v_exp_f32_e32 v179, v89
	v_sub_f32_e32 v89, v156, v202
	v_exp_f32_e32 v234, v89
	v_sub_f32_e32 v89, v158, v206
	v_exp_f32_e32 v236, v89
	v_sub_f32_e32 v89, v156, v203
	v_exp_f32_e32 v235, v89
	v_sub_f32_e32 v89, v158, v207
	v_exp_f32_e32 v237, v89
	v_sub_f32_e32 v89, v156, v80
	v_exp_f32_e32 v196, v89
	v_sub_f32_e32 v89, v158, v84
	v_exp_f32_e32 v194, v89
	v_sub_f32_e32 v89, v156, v81
	v_pk_mul_f32 v[178:179], v[178:179], v[102:103]
	v_cmp_ge_u32_e32 vcc, v199, v151
	v_exp_f32_e32 v197, v89
	v_sub_f32_e32 v89, v158, v85
	v_cndmask_b32_e32 v179, 0, v179, vcc
	v_cmp_ge_u32_e32 vcc, v198, v160
	v_exp_f32_e32 v195, v89
	v_sub_f32_e32 v89, v156, v82
	v_and_b32_e32 v187, 0xffff0000, v184
	v_cndmask_b32_e32 v178, 0, v178, vcc
	v_exp_f32_e32 v184, v89
	v_sub_f32_e32 v89, v158, v86
	v_pk_add_f32 v[178:179], v[182:183], v[178:179]
	v_exp_f32_e32 v182, v89
	v_sub_f32_e32 v89, v156, v83
	v_lshl_add_u64 v[114:115], v[164:165], 0, v[142:143]
	v_lshl_add_u64 v[116:117], v[164:165], 0, v[148:149]
	v_lshl_add_u64 v[166:167], v[164:165], 0, v[146:147]
	v_lshl_add_u64 v[168:169], v[164:165], 0, v[138:139]
	v_lshlrev_b32_e32 v170, 16, v185
	v_and_b32_e32 v171, 0xffff0000, v185
	v_exp_f32_e32 v185, v89
	v_sub_f32_e32 v89, v158, v87
	global_load_dwordx4 v[48:51], v[114:115], off offset:-64
	global_load_dwordx4 v[52:55], v[116:117], off offset:-64
	global_load_dwordx4 v[56:59], v[166:167], off offset:-64
	global_load_dwordx4 v[60:63], v[168:169], off offset:-64
	v_exp_f32_e32 v183, v89
	v_sub_f32_e32 v89, v157, v200
	v_exp_f32_e32 v89, v89
	v_sub_f32_e32 v93, v159, v204
	v_cmp_gt_u32_e32 vcc, v162, v198
	v_lshlrev_b32_e32 v238, 16, v208
	v_mul_f32_e32 v89, v89, v98
	v_exp_f32_e32 v98, v93
	v_sub_f32_e32 v93, v157, v201
	v_exp_f32_e32 v93, v93
	v_and_b32_e32 v239, 0xffff0000, v208
	v_pk_fma_f32 v[96:97], v[178:179], v[96:97], 0 op_sel_hi:[1,1,0]
	v_lshlrev_b32_e32 v208, 16, v209
	v_mul_f32_e32 v93, v93, v99
	v_cndmask_b32_e32 v201, 0, v93, vcc
	v_cmp_le_u32_e32 vcc, v198, v162
	v_cvt_pk_bf16_f32 v96, v96, v97
	v_and_b32_e32 v209, 0xffff0000, v209
	v_cndmask_b32_e32 v200, 0, v89, vcc
	v_sub_f32_e32 v89, v159, v205
	v_exp_f32_e32 v99, v89
	v_cmp_ge_u32_e32 vcc, v199, v121
	v_sub_f32_e32 v89, v157, v202
	v_or_b32_e32 v199, 3, v198
	v_pk_mul_f32 v[98:99], v[98:99], v[102:103]
	v_pk_mul_f32 v[204:205], v[216:217], v[104:105]
	v_cndmask_b32_e32 v99, 0, v99, vcc
	v_cmp_ge_u32_e32 vcc, v198, v162
	v_cmp_eq_u32_e64 s[0:1], v199, v163
	v_sub_f32_e32 v80, v157, v80
	v_cndmask_b32_e32 v98, 0, v98, vcc
	v_pk_add_f32 v[98:99], v[200:201], v[98:99]
	v_cmp_le_u32_e32 vcc, v199, v163
	v_pk_fma_f32 v[102:103], v[98:99], v[238:239], 0 op_sel_hi:[1,1,0]
	v_exp_f32_e32 v98, v89
	v_sub_f32_e32 v89, v159, v206
	v_exp_f32_e32 v200, v89
	v_sub_f32_e32 v89, v157, v203
	v_or_b32_e32 v206, 2, v198
	v_pk_mul_f32 v[202:203], v[214:215], v[100:101]
	v_exp_f32_e32 v99, v89
	v_cndmask_b32_e32 v203, 0, v203, vcc
	v_cmp_le_u32_e32 vcc, v206, v150
	v_sub_f32_e32 v89, v159, v207
	v_exp_f32_e32 v201, v89
	v_cndmask_b32_e32 v202, 0, v202, vcc
	v_cmp_ge_u32_e32 vcc, v199, v163
	v_pk_mul_f32 v[98:99], v[98:99], v[100:101]
	v_sub_f32_e32 v81, v157, v81
	v_cndmask_b32_e32 v205, 0, v205, vcc
	v_cmp_ge_u32_e32 vcc, v206, v150
	v_lshlrev_b32_e32 v192, 16, v210
	v_and_b32_e32 v193, 0xffff0000, v210
	v_cndmask_b32_e32 v204, 0, v204, vcc
	v_cmp_eq_u32_e32 vcc, v206, v150
	v_pk_add_f32 v[202:203], v[202:203], v[204:205]
	v_cndmask_b32_e64 v205, 0, v119, s[0:1]
	v_cndmask_b32_e32 v204, 0, v120, vcc
	v_pk_fma_f32 v[202:203], v[202:203], v[212:213], v[204:205]
	v_cmp_le_u32_e32 vcc, v199, v161
	v_cvt_pk_bf16_f32 v89, v202, v203
	v_pk_mul_f32 v[202:203], v[220:221], v[100:101]
	v_pk_mul_f32 v[204:205], v[222:223], v[104:105]
	v_cndmask_b32_e32 v203, 0, v203, vcc
	v_cmp_le_u32_e32 vcc, v206, v144
	v_cmp_eq_u32_e64 s[0:1], v199, v161
	v_lshlrev_b32_e32 v178, 16, v211
	v_cndmask_b32_e32 v202, 0, v202, vcc
	v_cmp_ge_u32_e32 vcc, v199, v161
	v_and_b32_e32 v179, 0xffff0000, v211
	v_add_u32_e32 v231, 32, v198
	v_cndmask_b32_e32 v205, 0, v205, vcc
	v_cmp_ge_u32_e32 vcc, v206, v144
	s_add_i32 s9, s9, 64
	v_lshl_add_u64 v[164:165], v[164:165], 0, s[14:15]
	v_cndmask_b32_e32 v204, 0, v204, vcc
	v_cmp_eq_u32_e32 vcc, v206, v144
	v_pk_add_f32 v[202:203], v[202:203], v[204:205]
	v_cndmask_b32_e64 v205, 0, v119, s[0:1]
	v_cndmask_b32_e32 v204, 0, v120, vcc
	v_pk_fma_f32 v[202:203], v[202:203], v[218:219], v[204:205]
	v_cmp_le_u32_e32 vcc, v199, v151
	v_cvt_pk_bf16_f32 v93, v202, v203
	v_pk_mul_f32 v[202:203], v[234:235], v[100:101]
	v_pk_mul_f32 v[204:205], v[236:237], v[104:105]
	v_cndmask_b32_e32 v203, 0, v203, vcc
	v_cmp_le_u32_e32 vcc, v206, v160
	v_pk_mul_f32 v[100:101], v[200:201], v[104:105]
	v_exp_f32_e32 v104, v80
	v_cndmask_b32_e32 v202, 0, v202, vcc
	v_cmp_ge_u32_e32 vcc, v199, v151
	v_sub_f32_e32 v80, v159, v84
	v_exp_f32_e32 v105, v81
	v_cndmask_b32_e32 v205, 0, v205, vcc
	v_cmp_ge_u32_e32 vcc, v206, v160
	v_sub_f32_e32 v81, v159, v85
	v_exp_f32_e32 v80, v80
	v_cndmask_b32_e32 v204, 0, v204, vcc
	v_cmp_le_u32_e32 vcc, v199, v121
	v_pk_add_f32 v[202:203], v[202:203], v[204:205]
	v_exp_f32_e32 v81, v81
	v_cndmask_b32_e32 v99, 0, v99, vcc
	v_cmp_le_u32_e32 vcc, v206, v162
	v_pk_fma_f32 v[202:203], v[202:203], v[232:233], 0 op_sel_hi:[1,1,0]
	s_cmpk_eq_i32 s9, 0x80
	v_cndmask_b32_e32 v98, 0, v98, vcc
	v_cmp_ge_u32_e32 vcc, v199, v121
	v_cvt_pk_bf16_f32 v97, v202, v203
	v_or_b32_e32 v199, 5, v198
	v_cndmask_b32_e32 v101, 0, v101, vcc
	v_cmp_ge_u32_e32 vcc, v206, v162
	ds_read_b128 v[200:203], v250 offset:1040
	ds_read_b128 v[204:207], v250 offset:1552
	v_cndmask_b32_e32 v100, 0, v100, vcc
	v_pk_add_f32 v[98:99], v[98:99], v[100:101]
	v_cmp_le_u32_e32 vcc, v199, v163
	v_pk_fma_f32 v[100:101], v[98:99], v[208:209], 0 op_sel_hi:[1,1,0]
	v_or_b32_e32 v208, 4, v198
	s_waitcnt lgkmcnt(1)
	v_pk_mul_f32 v[84:85], v[180:181], v[200:201]
	s_waitcnt lgkmcnt(0)
	v_pk_mul_f32 v[98:99], v[176:177], v[204:205]
	v_cndmask_b32_e32 v85, 0, v85, vcc
	v_cmp_le_u32_e32 vcc, v208, v150
	v_cmp_eq_u32_e64 s[0:1], v199, v163
	v_pk_mul_f32 v[80:81], v[80:81], v[204:205]
	v_cndmask_b32_e32 v84, 0, v84, vcc
	v_cmp_ge_u32_e32 vcc, v199, v163
	v_or_b32_e32 v176, 7, v198
	v_or_b32_e32 v177, 6, v198
	v_cndmask_b32_e32 v99, 0, v99, vcc
	v_cmp_ge_u32_e32 vcc, v208, v150
	s_nop 1
	v_cndmask_b32_e32 v98, 0, v98, vcc
	v_cmp_eq_u32_e32 vcc, v208, v150
	v_pk_add_f32 v[84:85], v[84:85], v[98:99]
	v_cndmask_b32_e64 v99, 0, v119, s[0:1]
	v_cndmask_b32_e32 v98, 0, v120, vcc
	v_pk_fma_f32 v[84:85], v[84:85], v[90:91], v[98:99]
	v_cmp_le_u32_e32 vcc, v199, v161
	v_cvt_pk_bf16_f32 v90, v84, v85
	v_pk_mul_f32 v[84:85], v[190:191], v[200:201]
	v_pk_mul_f32 v[98:99], v[188:189], v[204:205]
	v_cndmask_b32_e32 v85, 0, v85, vcc
	v_cmp_le_u32_e32 vcc, v208, v144
	v_cmp_eq_u32_e64 s[0:1], v199, v161
	s_nop 0
	v_cndmask_b32_e32 v84, 0, v84, vcc
	v_cmp_ge_u32_e32 vcc, v199, v161
	s_nop 1
	v_cndmask_b32_e32 v99, 0, v99, vcc
	v_cmp_ge_u32_e32 vcc, v208, v144
	s_nop 1
	v_cndmask_b32_e32 v98, 0, v98, vcc
	v_cmp_eq_u32_e32 vcc, v208, v144
	v_pk_add_f32 v[84:85], v[84:85], v[98:99]
	v_cndmask_b32_e64 v99, 0, v119, s[0:1]
	v_cndmask_b32_e32 v98, 0, v120, vcc
	v_pk_fma_f32 v[84:85], v[84:85], v[94:95], v[98:99]
	v_cmp_le_u32_e32 vcc, v199, v151
	v_cvt_pk_bf16_f32 v94, v84, v85
	v_pk_mul_f32 v[84:85], v[196:197], v[200:201]
	v_pk_mul_f32 v[98:99], v[194:195], v[204:205]
	v_cndmask_b32_e32 v85, 0, v85, vcc
	v_cmp_le_u32_e32 vcc, v208, v160
	v_cmp_eq_u32_e64 s[0:1], v176, v163
	s_nop 0
	v_cndmask_b32_e32 v84, 0, v84, vcc
	v_cmp_ge_u32_e32 vcc, v199, v151
	s_nop 1
	v_cndmask_b32_e32 v99, 0, v99, vcc
	v_cmp_ge_u32_e32 vcc, v208, v160
	s_nop 1
	v_cndmask_b32_e32 v98, 0, v98, vcc
	v_pk_add_f32 v[84:85], v[84:85], v[98:99]
	v_cmp_le_u32_e32 vcc, v199, v121
	v_pk_fma_f32 v[84:85], v[84:85], v[186:187], 0 op_sel_hi:[1,1,0]
	s_nop 0
	v_cvt_pk_bf16_f32 v98, v84, v85
	v_pk_mul_f32 v[84:85], v[104:105], v[200:201]
	v_pk_mul_f32 v[104:105], v[110:111], v[206:207]
	v_cndmask_b32_e32 v85, 0, v85, vcc
	v_cmp_le_u32_e32 vcc, v208, v162
	s_nop 1
	v_cndmask_b32_e32 v84, 0, v84, vcc
	v_cmp_ge_u32_e32 vcc, v199, v121
	s_nop 1
	v_cndmask_b32_e32 v81, 0, v81, vcc
	v_cmp_ge_u32_e32 vcc, v208, v162
	s_nop 1
	v_cndmask_b32_e32 v80, 0, v80, vcc
	v_pk_add_f32 v[80:81], v[84:85], v[80:81]
	v_cmp_le_u32_e32 vcc, v176, v163
	v_pk_fma_f32 v[84:85], v[80:81], v[192:193], 0 op_sel_hi:[1,1,0]
	v_sub_f32_e32 v81, v159, v86
	v_sub_f32_e32 v80, v157, v82
	v_exp_f32_e32 v82, v81
	v_sub_f32_e32 v81, v157, v83
	v_sub_f32_e32 v83, v159, v87
	v_pk_mul_f32 v[86:87], v[112:113], v[202:203]
	v_exp_f32_e32 v80, v80
	v_cndmask_b32_e32 v87, 0, v87, vcc
	v_cmp_le_u32_e32 vcc, v177, v150
	v_exp_f32_e32 v81, v81
	v_exp_f32_e32 v83, v83
	v_cndmask_b32_e32 v86, 0, v86, vcc
	v_cmp_ge_u32_e32 vcc, v176, v163
	v_pk_mul_f32 v[80:81], v[80:81], v[202:203]
	v_pk_mul_f32 v[82:83], v[82:83], v[206:207]
	v_cndmask_b32_e32 v105, 0, v105, vcc
	v_cmp_ge_u32_e32 vcc, v177, v150
	s_nop 1
	v_cndmask_b32_e32 v104, 0, v104, vcc
	v_cmp_eq_u32_e32 vcc, v177, v150
	v_pk_add_f32 v[86:87], v[86:87], v[104:105]
	v_cndmask_b32_e64 v105, 0, v119, s[0:1]
	v_cndmask_b32_e32 v104, 0, v120, vcc
	v_pk_fma_f32 v[86:87], v[86:87], v[106:107], v[104:105]
	v_cmp_le_u32_e32 vcc, v176, v161
	v_cvt_pk_bf16_f32 v91, v86, v87
	v_pk_mul_f32 v[86:87], v[174:175], v[202:203]
	v_cmp_eq_u32_e64 s[0:1], v176, v161
	v_cndmask_b32_e32 v87, 0, v87, vcc
	v_cmp_le_u32_e32 vcc, v177, v144
	s_waitcnt vmcnt(3)
	v_mfma_f32_16x16x32_bf16 v[72:75], v[48:51], v[88:91], v[72:75]
	v_cndmask_b32_e32 v86, 0, v86, vcc
	v_cmp_ge_u32_e32 vcc, v176, v161
	s_waitcnt vmcnt(2)
	v_mfma_f32_16x16x32_bf16 v[76:79], v[52:55], v[88:91], v[76:79]
	s_waitcnt vmcnt(1)
	v_mfma_f32_16x16x32_bf16 v[64:67], v[56:59], v[88:91], v[64:67]
	s_waitcnt vmcnt(0)
	v_mfma_f32_16x16x32_bf16 v[68:71], v[60:63], v[88:91], v[68:71]
	v_mul_f32_e64 v88, v172, v206
	v_mul_f32_e64 v89, v173, v207
	v_cndmask_b32_e32 v89, 0, v89, vcc
	v_cmp_ge_u32_e32 vcc, v177, v144
	s_nop 1
	v_cndmask_b32_e32 v88, 0, v88, vcc
	v_cmp_eq_u32_e32 vcc, v177, v144
	v_pk_add_f32 v[86:87], v[86:87], v[88:89]
	v_cndmask_b32_e64 v89, 0, v119, s[0:1]
	v_cndmask_b32_e32 v88, 0, v120, vcc
	v_pk_fma_f32 v[86:87], v[86:87], v[108:109], v[88:89]
	v_cmp_le_u32_e32 vcc, v176, v151
	v_cvt_pk_bf16_f32 v95, v86, v87
	v_pk_mul_f32 v[86:87], v[184:185], v[202:203]
	v_pk_mul_f32 v[88:89], v[182:183], v[206:207]
	v_cndmask_b32_e32 v87, 0, v87, vcc
	v_cmp_le_u32_e32 vcc, v177, v160
	v_mfma_f32_16x16x32_bf16 v[36:39], v[48:51], v[92:95], v[36:39]
	s_nop 0
	v_cndmask_b32_e32 v86, 0, v86, vcc
	v_cmp_ge_u32_e32 vcc, v176, v151
	v_mfma_f32_16x16x32_bf16 v[44:47], v[52:55], v[92:95], v[44:47]
	s_nop 0
	v_cndmask_b32_e32 v89, 0, v89, vcc
	v_cmp_ge_u32_e32 vcc, v177, v160
	v_mfma_f32_16x16x32_bf16 v[20:23], v[56:59], v[92:95], v[20:23]
	s_nop 0
	v_cndmask_b32_e32 v88, 0, v88, vcc
	v_cmp_le_u32_e32 vcc, v176, v121
	v_pk_add_f32 v[86:87], v[86:87], v[88:89]
	v_mfma_f32_16x16x32_bf16 v[32:35], v[60:63], v[92:95], v[32:35]
	v_cndmask_b32_e32 v81, 0, v81, vcc
	v_cmp_le_u32_e32 vcc, v177, v162
	v_pk_fma_f32 v[86:87], v[86:87], v[170:171], 0 op_sel_hi:[1,1,0]
	s_nop 0
	v_cndmask_b32_e32 v80, 0, v80, vcc
	v_cmp_ge_u32_e32 vcc, v176, v121
	v_cvt_pk_bf16_f32 v99, v86, v87
	s_nop 0
	v_cndmask_b32_e32 v83, 0, v83, vcc
	v_cmp_ge_u32_e32 vcc, v177, v162
	v_mfma_f32_16x16x32_bf16 v[8:11], v[48:51], v[96:99], v[8:11]
	s_nop 0
	v_cndmask_b32_e32 v82, 0, v82, vcc
	v_pk_add_f32 v[80:81], v[80:81], v[82:83]
	v_cvt_pk_bf16_f32 v82, v84, v85
	v_pk_fma_f32 v[86:87], v[80:81], v[178:179], 0 op_sel_hi:[1,1,0]
	v_cvt_pk_bf16_f32 v80, v102, v103
	v_cvt_pk_bf16_f32 v81, v100, v101
	v_cvt_pk_bf16_f32 v83, v86, v87
	v_mfma_f32_16x16x32_bf16 v[12:15], v[52:55], v[96:99], v[12:15]
	v_cmp_gt_u32_e32 vcc, v150, v231
	v_mfma_f32_16x16x32_bf16 v[0:3], v[56:59], v[96:99], v[0:3]
	v_mfma_f32_16x16x32_bf16 v[4:7], v[60:63], v[96:99], v[4:7]
	v_mfma_f32_16x16x32_bf16 v[28:31], v[48:51], v[80:83], v[28:31]
	v_mfma_f32_16x16x32_bf16 v[40:43], v[52:55], v[80:83], v[40:43]
	v_mfma_f32_16x16x32_bf16 v[16:19], v[56:59], v[80:83], v[16:19]
	v_mfma_f32_16x16x32_bf16 v[24:27], v[60:63], v[80:83], v[24:27]
	ds_read_b128 v[110:113], v250 offset:128
	ds_read_b128 v[84:87], v250 offset:144
	ds_read_b128 v[106:109], v250 offset:640
	ds_read_b128 v[80:83], v250 offset:656
	ds_read_b128 v[102:105], v250 offset:1152
	ds_read_b128 v[98:101], v250 offset:1664
	global_load_dwordx4 v[48:51], v[114:115], off
	global_load_dwordx4 v[52:55], v[116:117], off
	global_load_dwordx4 v[56:59], v[166:167], off
	global_load_dwordx4 v[60:63], v[168:169], off
	ds_read_b128 v[90:93], v240 offset:64
	ds_read_b128 v[114:117], v240 offset:4416
	s_waitcnt lgkmcnt(7)
	v_sub_f32_e32 v88, v152, v110
	v_exp_f32_e32 v88, v88
	s_waitcnt lgkmcnt(5)
	v_sub_f32_e32 v89, v154, v106
	s_waitcnt lgkmcnt(1)
	v_lshlrev_b32_e32 v166, 16, v93
	v_and_b32_e32 v167, 0xffff0000, v93
	v_sub_f32_e32 v93, v152, v111
	v_exp_f32_e32 v93, v93
	v_mul_f32_e32 v88, v88, v102
	v_lshlrev_b32_e32 v94, 16, v90
	v_and_b32_e32 v95, 0xffff0000, v90
	v_mul_f32_e32 v93, v93, v103
	v_cndmask_b32_e32 v97, 0, v93, vcc
	v_cmp_le_u32_e32 vcc, v231, v150
	v_lshlrev_b32_e32 v196, 16, v91
	v_and_b32_e32 v197, 0xffff0000, v91
	v_cndmask_b32_e32 v96, 0, v88, vcc
	v_sub_f32_e32 v88, v154, v107
	v_lshlrev_b32_e32 v90, 16, v92
	v_and_b32_e32 v91, 0xffff0000, v92
	v_exp_f32_e32 v92, v89
	v_exp_f32_e32 v93, v88
	v_sub_f32_e32 v88, v152, v112
	v_add_u32_e32 v89, 33, v198
	v_exp_f32_e32 v202, v88
	v_sub_f32_e32 v88, v154, v108
	v_pk_mul_f32 v[92:93], v[92:93], v[98:99]
	v_cmp_ge_u32_e32 vcc, v89, v163
	v_exp_f32_e32 v200, v88
	v_sub_f32_e32 v88, v152, v113
	v_cndmask_b32_e32 v93, 0, v93, vcc
	v_cmp_ge_u32_e32 vcc, v231, v150
	v_exp_f32_e32 v203, v88
	v_sub_f32_e32 v88, v154, v109
	v_cndmask_b32_e32 v92, 0, v92, vcc
	v_exp_f32_e32 v201, v88
	v_sub_f32_e32 v88, v152, v84
	v_pk_add_f32 v[92:93], v[96:97], v[92:93]
	v_exp_f32_e32 v184, v88
	v_sub_f32_e32 v88, v154, v80
	v_pk_fma_f32 v[92:93], v[92:93], v[94:95], 0 op_sel_hi:[1,1,0]
	v_exp_f32_e32 v94, v88
	v_sub_f32_e32 v88, v152, v85
	v_exp_f32_e32 v185, v88
	v_sub_f32_e32 v88, v154, v81
	v_exp_f32_e32 v95, v88
	v_sub_f32_e32 v88, v152, v86
	v_exp_f32_e32 v170, v88
	v_sub_f32_e32 v88, v154, v82
	v_exp_f32_e32 v168, v88
	v_sub_f32_e32 v88, v152, v87
	v_exp_f32_e32 v171, v88
	v_sub_f32_e32 v88, v154, v83
	v_exp_f32_e32 v169, v88
	v_cvt_pk_bf16_f32 v88, v92, v93
	s_waitcnt lgkmcnt(0)
	v_lshlrev_b32_e32 v92, 16, v114
	v_and_b32_e32 v93, 0xffff0000, v114
	v_sub_f32_e32 v114, v153, v111
	v_sub_f32_e32 v96, v153, v110
	v_exp_f32_e32 v114, v114
	v_exp_f32_e32 v96, v96
	v_cmp_gt_u32_e32 vcc, v144, v231
	v_lshlrev_b32_e32 v204, 16, v115
	v_mul_f32_e32 v114, v114, v103
	v_and_b32_e32 v205, 0xffff0000, v115
	v_mul_f32_e32 v97, v96, v102
	v_cndmask_b32_e32 v115, 0, v114, vcc
	v_cmp_le_u32_e32 vcc, v231, v144
	v_sub_f32_e32 v96, v155, v106
	v_exp_f32_e32 v96, v96
	v_cndmask_b32_e32 v114, 0, v97, vcc
	v_sub_f32_e32 v97, v155, v107
	v_exp_f32_e32 v97, v97
	v_cmp_ge_u32_e32 vcc, v89, v161
	v_lshlrev_b32_e32 v186, 16, v116
	v_and_b32_e32 v187, 0xffff0000, v116
	v_pk_mul_f32 v[96:97], v[96:97], v[98:99]
	v_lshlrev_b32_e32 v172, 16, v117
	v_cndmask_b32_e32 v97, 0, v97, vcc
	v_cmp_ge_u32_e32 vcc, v231, v144
	v_and_b32_e32 v173, 0xffff0000, v117
	v_cmp_eq_u32_e64 s[0:1], v89, v151
	v_cndmask_b32_e32 v96, 0, v96, vcc
	v_pk_add_f32 v[96:97], v[114:115], v[96:97]
	ds_read_b128 v[114:117], v240 offset:8768
	v_pk_fma_f32 v[92:93], v[96:97], v[92:93], 0 op_sel_hi:[1,1,0]
	v_sub_f32_e32 v96, v153, v112
	v_cvt_pk_bf16_f32 v92, v92, v93
	v_sub_f32_e32 v93, v156, v110
	s_waitcnt lgkmcnt(0)
	v_lshlrev_b32_e32 v210, 16, v115
	v_and_b32_e32 v211, 0xffff0000, v115
	v_sub_f32_e32 v115, v156, v111
	v_exp_f32_e32 v115, v115
	v_exp_f32_e32 v93, v93
	v_exp_f32_e32 v208, v96
	v_sub_f32_e32 v96, v155, v108
	v_exp_f32_e32 v206, v96
	v_sub_f32_e32 v96, v153, v113
	v_exp_f32_e32 v209, v96
	v_sub_f32_e32 v96, v155, v109
	v_cmp_gt_u32_e32 vcc, v160, v231
	v_mul_f32_e32 v115, v115, v103
	v_exp_f32_e32 v207, v96
	v_sub_f32_e32 v96, v153, v84
	v_lshlrev_b32_e32 v178, 16, v117
	v_and_b32_e32 v179, 0xffff0000, v117
	v_mul_f32_e32 v93, v93, v102
	v_cndmask_b32_e32 v117, 0, v115, vcc
	v_cmp_le_u32_e32 vcc, v231, v160
	v_exp_f32_e32 v190, v96
	v_sub_f32_e32 v96, v155, v80
	v_lshlrev_b32_e32 v192, 16, v116
	v_and_b32_e32 v193, 0xffff0000, v116
	v_cndmask_b32_e32 v116, 0, v93, vcc
	v_sub_f32_e32 v93, v158, v107
	v_exp_f32_e32 v188, v96
	v_sub_f32_e32 v96, v153, v85
	v_exp_f32_e32 v115, v93
	v_sub_f32_e32 v93, v156, v112
	v_exp_f32_e32 v191, v96
	v_sub_f32_e32 v96, v155, v81
	v_exp_f32_e32 v214, v93
	v_sub_f32_e32 v93, v158, v108
	v_exp_f32_e32 v189, v96
	v_sub_f32_e32 v96, v153, v86
	v_exp_f32_e32 v212, v93
	v_sub_f32_e32 v93, v156, v113
	v_exp_f32_e32 v176, v96
	v_sub_f32_e32 v96, v155, v82
	v_exp_f32_e32 v215, v93
	v_sub_f32_e32 v93, v158, v109
	v_exp_f32_e32 v174, v96
	v_sub_f32_e32 v96, v153, v87
	v_exp_f32_e32 v213, v93
	v_sub_f32_e32 v93, v156, v84
	v_exp_f32_e32 v177, v96
	v_sub_f32_e32 v96, v155, v83
	v_exp_f32_e32 v198, v93
	v_sub_f32_e32 v93, v158, v80
	v_exp_f32_e32 v175, v96
	v_lshlrev_b32_e32 v96, 16, v114
	v_and_b32_e32 v97, 0xffff0000, v114
	v_sub_f32_e32 v114, v158, v106
	v_exp_f32_e32 v194, v93
	v_sub_f32_e32 v93, v156, v85
	v_exp_f32_e32 v114, v114
	v_exp_f32_e32 v199, v93
	v_sub_f32_e32 v93, v158, v81
	v_exp_f32_e32 v195, v93
	v_sub_f32_e32 v93, v156, v86
	v_exp_f32_e32 v182, v93
	v_sub_f32_e32 v93, v158, v82
	v_exp_f32_e32 v180, v93
	v_sub_f32_e32 v93, v156, v87
	v_pk_mul_f32 v[114:115], v[114:115], v[98:99]
	v_cmp_ge_u32_e32 vcc, v89, v151
	v_exp_f32_e32 v183, v93
	v_sub_f32_e32 v93, v158, v83
	v_cndmask_b32_e32 v115, 0, v115, vcc
	v_cmp_ge_u32_e32 vcc, v231, v160
	v_exp_f32_e32 v181, v93
	v_sub_f32_e32 v93, v157, v110
	v_cndmask_b32_e32 v114, 0, v114, vcc
	v_cmp_eq_u32_e32 vcc, v231, v160
	v_exp_f32_e32 v93, v93
	v_pk_add_f32 v[114:115], v[116:117], v[114:115]
	v_cndmask_b32_e64 v117, 0, v119, s[0:1]
	v_cndmask_b32_e32 v116, 0, v120, vcc
	v_pk_fma_f32 v[96:97], v[114:115], v[96:97], v[116:117]
	v_mul_f32_e32 v93, v93, v102
	v_cvt_pk_bf16_f32 v96, v96, v97
	v_sub_f32_e32 v97, v159, v106
	v_exp_f32_e32 v102, v97
	v_sub_f32_e32 v97, v157, v111
	v_exp_f32_e32 v97, v97
	v_cmp_gt_u32_e32 vcc, v162, v231
	ds_read_b128 v[114:117], v240 offset:13120
	v_cmp_eq_u32_e64 s[0:1], v89, v121
	v_mul_f32_e32 v97, v97, v103
	v_cndmask_b32_e32 v111, 0, v97, vcc
	v_cmp_le_u32_e32 vcc, v231, v162
	s_waitcnt lgkmcnt(0)
	v_lshlrev_b32_e32 v220, 16, v114
	v_and_b32_e32 v221, 0xffff0000, v114
	v_cndmask_b32_e32 v110, 0, v93, vcc
	v_sub_f32_e32 v93, v159, v107
	v_exp_f32_e32 v103, v93
	v_cmp_ge_u32_e32 vcc, v89, v121
	v_sub_f32_e32 v89, v157, v112
	v_or_b32_e32 v112, 3, v231
	v_pk_mul_f32 v[98:99], v[102:103], v[98:99]
	v_cndmask_b32_e64 v103, 0, v119, s[0:1]
	v_cndmask_b32_e32 v99, 0, v99, vcc
	v_cmp_ge_u32_e32 vcc, v231, v162
	v_pk_mul_f32 v[106:107], v[202:203], v[104:105]
	v_cmp_eq_u32_e64 s[0:1], v112, v151
	v_cndmask_b32_e32 v98, 0, v98, vcc
	v_cmp_eq_u32_e32 vcc, v231, v162
	v_pk_add_f32 v[98:99], v[110:111], v[98:99]
	v_lshlrev_b32_e32 v218, 16, v115
	v_cndmask_b32_e32 v102, 0, v120, vcc
	v_pk_fma_f32 v[110:111], v[98:99], v[220:221], v[102:103]
	v_exp_f32_e32 v98, v89
	v_sub_f32_e32 v89, v159, v108
	v_exp_f32_e32 v102, v89
	v_sub_f32_e32 v89, v157, v113
	v_or_b32_e32 v113, 2, v231
	v_cmp_le_u32_e32 vcc, v112, v163
	v_exp_f32_e32 v99, v89
	v_sub_f32_e32 v89, v159, v109
	v_cndmask_b32_e32 v107, 0, v107, vcc
	v_cmp_le_u32_e32 vcc, v113, v150
	v_pk_mul_f32 v[108:109], v[200:201], v[100:101]
	v_exp_f32_e32 v103, v89
	v_cndmask_b32_e32 v106, 0, v106, vcc
	v_cmp_ge_u32_e32 vcc, v112, v163
	v_pk_mul_f32 v[98:99], v[98:99], v[104:105]
	v_and_b32_e32 v219, 0xffff0000, v115
	v_cndmask_b32_e32 v109, 0, v109, vcc
	v_cmp_ge_u32_e32 vcc, v113, v150
	v_lshlrev_b32_e32 v216, 16, v116
	v_and_b32_e32 v217, 0xffff0000, v116
	v_cndmask_b32_e32 v108, 0, v108, vcc
	v_pk_add_f32 v[106:107], v[106:107], v[108:109]
	v_cmp_le_u32_e32 vcc, v112, v161
	v_pk_fma_f32 v[106:107], v[106:107], v[196:197], 0 op_sel_hi:[1,1,0]
	v_pk_mul_f32 v[108:109], v[206:207], v[100:101]
	v_cvt_pk_bf16_f32 v89, v106, v107
	v_pk_mul_f32 v[106:107], v[208:209], v[104:105]
	v_or_b32_e32 v116, 5, v231
	v_cndmask_b32_e32 v107, 0, v107, vcc
	v_cmp_le_u32_e32 vcc, v113, v144
	v_lshlrev_b32_e32 v114, 16, v117
	v_and_b32_e32 v115, 0xffff0000, v117
	v_cndmask_b32_e32 v106, 0, v106, vcc
	v_cmp_ge_u32_e32 vcc, v112, v161
	v_or_b32_e32 v117, 4, v231
	v_sub_f32_e32 v84, v157, v84
	v_cndmask_b32_e32 v109, 0, v109, vcc
	v_cmp_ge_u32_e32 vcc, v113, v144
	v_sub_f32_e32 v85, v157, v85
	v_exp_f32_e32 v84, v84
	v_cndmask_b32_e32 v108, 0, v108, vcc
	v_pk_add_f32 v[106:107], v[106:107], v[108:109]
	v_cmp_le_u32_e32 vcc, v112, v151
	v_pk_fma_f32 v[106:107], v[106:107], v[204:205], 0 op_sel_hi:[1,1,0]
	v_pk_mul_f32 v[108:109], v[212:213], v[100:101]
	v_cvt_pk_bf16_f32 v93, v106, v107
	v_pk_mul_f32 v[106:107], v[214:215], v[104:105]
	v_pk_mul_f32 v[100:101], v[102:103], v[100:101]
	v_cndmask_b32_e32 v107, 0, v107, vcc
	v_cmp_le_u32_e32 vcc, v113, v160
	v_exp_f32_e32 v85, v85
	v_sub_f32_e32 v80, v159, v80
	v_cndmask_b32_e32 v106, 0, v106, vcc
	v_cmp_ge_u32_e32 vcc, v112, v151
	v_sub_f32_e32 v81, v159, v81
	v_exp_f32_e32 v80, v80
	v_cndmask_b32_e32 v109, 0, v109, vcc
	v_cmp_ge_u32_e32 vcc, v113, v160
	v_exp_f32_e32 v81, v81
	v_sub_f32_e32 v82, v159, v82
	v_cndmask_b32_e32 v108, 0, v108, vcc
	v_cmp_eq_u32_e32 vcc, v113, v160
	v_pk_add_f32 v[106:107], v[106:107], v[108:109]
	v_cndmask_b32_e64 v109, 0, v119, s[0:1]
	v_cndmask_b32_e32 v108, 0, v120, vcc
	v_cmp_le_u32_e32 vcc, v112, v121
	v_cmp_eq_u32_e64 s[0:1], v112, v121
	v_pk_fma_f32 v[106:107], v[106:107], v[210:211], v[108:109]
	v_cndmask_b32_e32 v99, 0, v99, vcc
	v_cmp_le_u32_e32 vcc, v113, v162
	v_cvt_pk_bf16_f32 v97, v106, v107
	v_sub_f32_e32 v83, v159, v83
	v_cndmask_b32_e32 v98, 0, v98, vcc
	v_cmp_ge_u32_e32 vcc, v112, v121
	v_exp_f32_e32 v82, v82
	v_exp_f32_e32 v83, v83
	v_cndmask_b32_e32 v101, 0, v101, vcc
	v_cmp_ge_u32_e32 vcc, v113, v162
	v_add_u32_e32 v240, 0x80, v240
	s_nop 0
	v_cndmask_b32_e32 v100, 0, v100, vcc
	v_cmp_eq_u32_e32 vcc, v113, v162
	v_pk_add_f32 v[98:99], v[98:99], v[100:101]
	v_cndmask_b32_e64 v101, 0, v119, s[0:1]
	v_cndmask_b32_e32 v100, 0, v120, vcc
	v_pk_fma_f32 v[108:109], v[98:99], v[218:219], v[100:101]
	ds_read_b128 v[104:107], v250 offset:1168
	ds_read_b128 v[100:103], v250 offset:1680
	v_cmp_le_u32_e32 vcc, v116, v163
	v_cmp_eq_u32_e64 s[0:1], v116, v151
	v_add_u32_e32 v250, 0x100, v250
	s_waitcnt lgkmcnt(1)
	v_pk_mul_f32 v[98:99], v[184:185], v[104:105]
	s_waitcnt lgkmcnt(0)
	v_pk_mul_f32 v[94:95], v[94:95], v[100:101]
	v_cndmask_b32_e32 v99, 0, v99, vcc
	v_cmp_le_u32_e32 vcc, v117, v150
	v_pk_mul_f32 v[112:113], v[194:195], v[100:101]
	v_pk_mul_f32 v[84:85], v[84:85], v[104:105]
	v_cndmask_b32_e32 v98, 0, v98, vcc
	v_cmp_ge_u32_e32 vcc, v116, v163
	v_pk_mul_f32 v[80:81], v[80:81], v[100:101]
	v_pk_mul_f32 v[82:83], v[82:83], v[102:103]
	v_cndmask_b32_e32 v95, 0, v95, vcc
	v_cmp_ge_u32_e32 vcc, v117, v150
	s_nop 1
	v_cndmask_b32_e32 v94, 0, v94, vcc
	v_pk_add_f32 v[94:95], v[98:99], v[94:95]
	v_cmp_le_u32_e32 vcc, v116, v161
	v_pk_fma_f32 v[90:91], v[94:95], v[90:91], 0 op_sel_hi:[1,1,0]
	v_pk_mul_f32 v[94:95], v[190:191], v[104:105]
	v_pk_mul_f32 v[98:99], v[188:189], v[100:101]
	v_cndmask_b32_e32 v95, 0, v95, vcc
	v_cmp_le_u32_e32 vcc, v117, v144
	v_pk_mul_f32 v[100:101], v[170:171], v[106:107]
	v_cvt_pk_bf16_f32 v90, v90, v91
	v_cndmask_b32_e32 v94, 0, v94, vcc
	v_cmp_ge_u32_e32 vcc, v116, v161
	s_nop 1
	v_cndmask_b32_e32 v99, 0, v99, vcc
	v_cmp_ge_u32_e32 vcc, v117, v144
	s_nop 1
	v_cndmask_b32_e32 v98, 0, v98, vcc
	v_pk_add_f32 v[94:95], v[94:95], v[98:99]
	v_pk_mul_f32 v[98:99], v[198:199], v[104:105]
	v_cmp_le_u32_e32 vcc, v116, v151
	v_pk_mul_f32 v[104:105], v[168:169], v[102:103]
	v_pk_fma_f32 v[94:95], v[94:95], v[186:187], 0 op_sel_hi:[1,1,0]
	v_cndmask_b32_e32 v99, 0, v99, vcc
	v_cmp_le_u32_e32 vcc, v117, v160
	v_cvt_pk_bf16_f32 v94, v94, v95
	s_nop 0
	v_cndmask_b32_e32 v98, 0, v98, vcc
	v_cmp_ge_u32_e32 vcc, v116, v151
	s_nop 1
	v_cndmask_b32_e32 v113, 0, v113, vcc
	v_cmp_ge_u32_e32 vcc, v117, v160
	s_nop 1
	v_cndmask_b32_e32 v112, 0, v112, vcc
	v_cmp_eq_u32_e32 vcc, v117, v160
	v_pk_add_f32 v[98:99], v[98:99], v[112:113]
	v_cndmask_b32_e64 v113, 0, v119, s[0:1]
	v_cndmask_b32_e32 v112, 0, v120, vcc
	v_cmp_le_u32_e32 vcc, v116, v121
	v_cmp_eq_u32_e64 s[0:1], v116, v121
	v_pk_fma_f32 v[98:99], v[98:99], v[192:193], v[112:113]
	v_cndmask_b32_e32 v85, 0, v85, vcc
	v_cmp_le_u32_e32 vcc, v117, v162
	v_cvt_pk_bf16_f32 v98, v98, v99
	s_nop 0
	v_cndmask_b32_e32 v84, 0, v84, vcc
	v_cmp_ge_u32_e32 vcc, v116, v121
	s_nop 1
	v_cndmask_b32_e32 v81, 0, v81, vcc
	v_cmp_ge_u32_e32 vcc, v117, v162
	s_nop 1
	v_cndmask_b32_e32 v80, 0, v80, vcc
	v_cmp_eq_u32_e32 vcc, v117, v162
	v_pk_add_f32 v[80:81], v[84:85], v[80:81]
	v_cndmask_b32_e64 v85, 0, v119, s[0:1]
	v_cndmask_b32_e32 v84, 0, v120, vcc
	v_pk_fma_f32 v[80:81], v[80:81], v[216:217], v[84:85]
	v_sub_f32_e32 v84, v157, v86
	v_or_b32_e32 v86, 7, v231
	v_sub_f32_e32 v85, v157, v87
	v_or_b32_e32 v87, 6, v231
	v_cmp_le_u32_e32 vcc, v86, v163
	v_exp_f32_e32 v84, v84
	v_exp_f32_e32 v85, v85
	v_cndmask_b32_e32 v101, 0, v101, vcc
	v_cmp_le_u32_e32 vcc, v87, v150
	v_cmp_eq_u32_e64 s[0:1], v86, v151
	v_pk_mul_f32 v[84:85], v[84:85], v[106:107]
	v_cndmask_b32_e32 v100, 0, v100, vcc
	v_cmp_ge_u32_e32 vcc, v86, v163
	s_nop 1
	v_cndmask_b32_e32 v105, 0, v105, vcc
	v_cmp_ge_u32_e32 vcc, v87, v150
	s_nop 1
	v_cndmask_b32_e32 v104, 0, v104, vcc
	v_pk_add_f32 v[100:101], v[100:101], v[104:105]
	v_cmp_le_u32_e32 vcc, v86, v161
	v_pk_fma_f32 v[100:101], v[100:101], v[166:167], 0 op_sel_hi:[1,1,0]
	s_nop 0
	v_cvt_pk_bf16_f32 v91, v100, v101
	s_waitcnt vmcnt(3)
	s_nop 0
	v_mfma_f32_16x16x32_bf16 v[72:75], v[48:51], v[88:91], v[72:75]
	s_waitcnt vmcnt(2)
	v_mfma_f32_16x16x32_bf16 v[76:79], v[52:55], v[88:91], v[76:79]
	s_waitcnt vmcnt(1)
	v_mfma_f32_16x16x32_bf16 v[64:67], v[56:59], v[88:91], v[64:67]
	s_waitcnt vmcnt(0)
	v_mfma_f32_16x16x32_bf16 v[68:71], v[60:63], v[88:91], v[68:71]
	v_mul_f32_e64 v88, v176, v106
	v_mul_f32_e64 v89, v177, v107
	v_pk_mul_f32 v[90:91], v[174:175], v[102:103]
	v_cndmask_b32_e32 v89, 0, v89, vcc
	v_cmp_le_u32_e32 vcc, v87, v144
	s_nop 1
	v_cndmask_b32_e32 v88, 0, v88, vcc
	v_cmp_ge_u32_e32 vcc, v86, v161
	s_nop 1
	v_cndmask_b32_e32 v91, 0, v91, vcc
	v_cmp_ge_u32_e32 vcc, v87, v144
	s_nop 1
	v_cndmask_b32_e32 v90, 0, v90, vcc
	v_pk_add_f32 v[88:89], v[88:89], v[90:91]
	v_cmp_le_u32_e32 vcc, v86, v151
	v_pk_fma_f32 v[88:89], v[88:89], v[172:173], 0 op_sel_hi:[1,1,0]
	v_pk_mul_f32 v[90:91], v[180:181], v[102:103]
	v_cvt_pk_bf16_f32 v95, v88, v89
	v_pk_mul_f32 v[88:89], v[182:183], v[106:107]
	s_nop 0
	v_cndmask_b32_e32 v89, 0, v89, vcc
	v_cmp_le_u32_e32 vcc, v87, v160
	v_mfma_f32_16x16x32_bf16 v[36:39], v[48:51], v[92:95], v[36:39]
	s_nop 0
	v_cndmask_b32_e32 v88, 0, v88, vcc
	v_cmp_ge_u32_e32 vcc, v86, v151
	v_mfma_f32_16x16x32_bf16 v[44:47], v[52:55], v[92:95], v[44:47]
	s_nop 0
	v_cndmask_b32_e32 v91, 0, v91, vcc
	v_cmp_ge_u32_e32 vcc, v87, v160
	v_mfma_f32_16x16x32_bf16 v[20:23], v[56:59], v[92:95], v[20:23]
	s_nop 0
	v_cndmask_b32_e32 v90, 0, v90, vcc
	v_cmp_eq_u32_e32 vcc, v87, v160
	v_pk_add_f32 v[88:89], v[88:89], v[90:91]
	v_cndmask_b32_e64 v91, 0, v119, s[0:1]
	v_cndmask_b32_e32 v90, 0, v120, vcc
	v_cmp_le_u32_e32 vcc, v86, v121
	v_cmp_eq_u32_e64 s[0:1], v86, v121
	v_pk_fma_f32 v[88:89], v[88:89], v[178:179], v[90:91]
	v_cndmask_b32_e32 v85, 0, v85, vcc
	v_cmp_le_u32_e32 vcc, v87, v162
	v_cvt_pk_bf16_f32 v99, v88, v89
	v_mfma_f32_16x16x32_bf16 v[32:35], v[60:63], v[92:95], v[32:35]
	v_cndmask_b32_e32 v84, 0, v84, vcc
	v_cmp_ge_u32_e32 vcc, v86, v121
	v_mfma_f32_16x16x32_bf16 v[8:11], v[48:51], v[96:99], v[8:11]
	s_nop 0
	v_cndmask_b32_e32 v83, 0, v83, vcc
	v_cmp_ge_u32_e32 vcc, v87, v162
	v_mfma_f32_16x16x32_bf16 v[12:15], v[52:55], v[96:99], v[12:15]
	s_nop 0
	v_cndmask_b32_e32 v82, 0, v82, vcc
	v_cmp_eq_u32_e32 vcc, v87, v162
	v_pk_add_f32 v[82:83], v[84:85], v[82:83]
	v_cndmask_b32_e64 v85, 0, v119, s[0:1]
	v_cndmask_b32_e32 v84, 0, v120, vcc
	v_pk_fma_f32 v[86:87], v[82:83], v[114:115], v[84:85]
	v_cvt_pk_bf16_f32 v82, v110, v111
	v_cvt_pk_bf16_f32 v83, v108, v109
	v_cvt_pk_bf16_f32 v84, v80, v81
	v_cvt_pk_bf16_f32 v85, v86, v87
	v_mfma_f32_16x16x32_bf16 v[0:3], v[56:59], v[96:99], v[0:3]
	v_mfma_f32_16x16x32_bf16 v[4:7], v[60:63], v[96:99], v[4:7]
	v_mfma_f32_16x16x32_bf16 v[28:31], v[48:51], v[82:85], v[28:31]
	v_mfma_f32_16x16x32_bf16 v[40:43], v[52:55], v[82:85], v[40:43]
	v_mfma_f32_16x16x32_bf16 v[16:19], v[56:59], v[82:85], v[16:19]
	v_mfma_f32_16x16x32_bf16 v[24:27], v[60:63], v[82:85], v[24:27]
	s_cbranch_scc0 .LBB0_852
	v_or_b32_e32 v54, s8, v249
	v_ashrrev_i32_e32 v55, 31, v54
	v_lshlrev_b64 v[48:49], 11, v[54:55]
	v_lshl_add_u64 v[58:59], v[124:125], 0, v[48:49]
	global_load_dwordx4 v[182:185], v[126:127], off
	global_load_dwordx4 v[186:189], v[126:127], off offset:16
	global_load_dwordx4 v[190:193], v[126:127], off offset:128
	global_load_dwordx4 v[194:197], v[126:127], off offset:144
	global_load_dwordx4 v[150:153], v[58:59], off
	global_load_dwordx4 v[154:157], v[58:59], off offset:64
	s_mov_b32 s0, 0x8000
	s_mov_b32 s1, 0
	v_lshl_add_u64 v[198:199], v[58:59], 0, s[0:1]
	global_load_dwordx4 v[158:161], v[198:199], off
	global_load_dwordx4 v[162:165], v[198:199], off offset:64
	s_mov_b32 s0, 0x10000
	s_mov_b32 s1, 0
	v_lshl_add_u64 v[200:201], v[58:59], 0, s[0:1]
	global_load_dwordx4 v[166:169], v[200:201], off
	global_load_dwordx4 v[170:173], v[200:201], off offset:64
	s_mov_b32 s0, 0x18000
	s_mov_b32 s1, 0
	v_lshl_add_u64 v[202:203], v[58:59], 0, s[0:1]
	global_load_dwordx4 v[174:177], v[202:203], off
	global_load_dwordx4 v[178:181], v[202:203], off offset:64
	s_waitcnt vmcnt(7)
	v_mov_b32_e32 v60, v150
	v_mov_b32_e32 v61, v151
	v_mov_b32_e32 v62, v152
	v_mov_b32_e32 v63, v153
	v_lshlrev_b32_e32 v48, 16, v60
	v_and_b32_e32 v49, 0xffff0000, v60
	v_mul_f32_e32 v50, 0xbfb8aa3b, v48
	v_mul_f32_e32 v51, 0xbfb8aa3b, v49
	v_exp_f32_e32 v50, v50
	v_exp_f32_e32 v51, v51
	s_waitcnt vmcnt(6)
	v_mov_b32_e32 v80, v154
	v_mov_b32_e32 v81, v155
	v_mov_b32_e32 v82, v156
	v_mov_b32_e32 v83, v157
	v_lshlrev_b32_e32 v58, 16, v80
	v_and_b32_e32 v59, 0xffff0000, v80
	v_add_f32_e32 v50, 1.0, v50
	v_add_f32_e32 v51, 1.0, v51
	v_rcp_f32_e32 v50, v50
	v_rcp_f32_e32 v51, v51
	s_nop 0
	v_pk_mul_f32 v[48:49], v[50:51], v[48:49]
	v_lshlrev_b32_e32 v50, 16, v61
	v_and_b32_e32 v51, 0xffff0000, v61
	v_mul_f32_e32 v52, 0xbfb8aa3b, v50
	v_mul_f32_e32 v53, 0xbfb8aa3b, v51
	v_exp_f32_e32 v52, v52
	v_exp_f32_e32 v53, v53
	v_pk_mul_f32 v[48:49], v[72:73], v[48:49]
	v_add_f32_e32 v52, 1.0, v52
	v_add_f32_e32 v53, 1.0, v53
	v_rcp_f32_e32 v52, v52
	v_rcp_f32_e32 v53, v53
	s_nop 0
	v_pk_mul_f32 v[50:51], v[52:53], v[50:51]
	v_lshlrev_b32_e32 v52, 16, v62
	v_mul_f32_e32 v55, 0xbfb8aa3b, v52
	v_exp_f32_e32 v55, v55
	v_and_b32_e32 v53, 0xffff0000, v62
	v_pk_mul_f32 v[50:51], v[74:75], v[50:51]
	v_pk_mul_f32 v[74:75], v[48:49], v[48:49]
	v_add_f32_e32 v55, 1.0, v55
	v_rcp_f32_e32 v56, v55
	v_mul_f32_e32 v55, 0xbfb8aa3b, v53
	v_exp_f32_e32 v55, v55
	v_pk_mul_f32 v[72:73], v[50:51], v[50:51]
	v_add_f32_e32 v74, v74, v75
	v_add_f32_e32 v72, v74, v72
	v_add_f32_e32 v55, 1.0, v55
	v_rcp_f32_e32 v57, v55
	v_add_f32_e32 v72, v73, v72
	v_pk_mul_f32 v[52:53], v[56:57], v[52:53]
	v_lshlrev_b32_e32 v56, 16, v63
	v_mul_f32_e32 v55, 0xbfb8aa3b, v56
	v_exp_f32_e32 v55, v55
	v_and_b32_e32 v57, 0xffff0000, v63
	v_pk_mul_f32 v[52:53], v[76:77], v[52:53]
	v_add_f32_e32 v55, 1.0, v55
	v_rcp_f32_e32 v60, v55
	v_mul_f32_e32 v55, 0xbfb8aa3b, v57
	v_exp_f32_e32 v55, v55
	s_nop 0
	v_add_f32_e32 v55, 1.0, v55
	v_rcp_f32_e32 v61, v55
	v_mul_f32_e32 v55, 0xbfb8aa3b, v58
	v_exp_f32_e32 v55, v55
	v_pk_mul_f32 v[56:57], v[60:61], v[56:57]
	s_nop 0
	v_pk_mul_f32 v[56:57], v[78:79], v[56:57]
	v_add_f32_e32 v55, 1.0, v55
	v_rcp_f32_e32 v60, v55
	v_mul_f32_e32 v55, 0xbfb8aa3b, v59
	v_exp_f32_e32 v55, v55
	v_pk_mul_f32 v[78:79], v[52:53], v[52:53]
	v_pk_mul_f32 v[76:77], v[56:57], v[56:57]
	v_add_f32_e32 v55, 1.0, v55
	v_rcp_f32_e32 v61, v55
	s_nop 0
	v_pk_mul_f32 v[58:59], v[60:61], v[58:59]
	v_lshlrev_b32_e32 v60, 16, v81
	v_mul_f32_e32 v55, 0xbfb8aa3b, v60
	v_exp_f32_e32 v55, v55
	v_and_b32_e32 v61, 0xffff0000, v81
	v_pk_mul_f32 v[58:59], v[64:65], v[58:59]
	v_add_f32_e32 v55, 1.0, v55
	v_rcp_f32_e32 v62, v55
	v_mul_f32_e32 v55, 0xbfb8aa3b, v61
	v_exp_f32_e32 v55, v55
	v_pk_mul_f32 v[80:81], v[58:59], v[58:59]
	v_add_f32_e32 v55, 1.0, v55
	v_rcp_f32_e32 v63, v55
	s_nop 0
	v_pk_mul_f32 v[60:61], v[62:63], v[60:61]
	v_lshlrev_b32_e32 v62, 16, v82
	v_mul_f32_e32 v55, 0xbfb8aa3b, v62
	v_exp_f32_e32 v55, v55
	v_and_b32_e32 v63, 0xffff0000, v82
	v_pk_mul_f32 v[60:61], v[66:67], v[60:61]
	v_add_f32_e32 v55, 1.0, v55
	v_rcp_f32_e32 v64, v55
	v_mul_f32_e32 v55, 0xbfb8aa3b, v63
	v_exp_f32_e32 v55, v55
	v_pk_mul_f32 v[66:67], v[60:61], v[60:61]
	v_add_f32_e32 v55, 1.0, v55
	v_rcp_f32_e32 v65, v55
	s_nop 0
	v_pk_mul_f32 v[62:63], v[64:65], v[62:63]
	v_lshlrev_b32_e32 v64, 16, v83
	v_mul_f32_e32 v55, 0xbfb8aa3b, v64
	v_exp_f32_e32 v55, v55
	v_and_b32_e32 v65, 0xffff0000, v83
	v_pk_mul_f32 v[62:63], v[68:69], v[62:63]
	v_add_f32_e32 v55, 1.0, v55
	v_rcp_f32_e32 v68, v55
	v_mul_f32_e32 v55, 0xbfb8aa3b, v65
	v_exp_f32_e32 v55, v55
	s_nop 0
	v_add_f32_e32 v55, 1.0, v55
	v_rcp_f32_e32 v69, v55
	v_add_f32_e32 v55, v78, v79
	v_add_f32_e32 v55, v55, v76
	v_add_f32_e32 v55, v77, v55
	v_add_f32_e32 v55, v72, v55
	v_add_f32_e32 v72, v80, v81
	v_pk_mul_f32 v[64:65], v[68:69], v[64:65]
	v_add_f32_e32 v66, v72, v66
	v_pk_mul_f32 v[64:65], v[70:71], v[64:65]
	v_pk_mul_f32 v[68:69], v[62:63], v[62:63]
	v_add_f32_e32 v66, v67, v66
	v_pk_mul_f32 v[70:71], v[64:65], v[64:65]
	v_add_f32_e32 v55, v55, v66
	v_add_f32_e32 v66, v68, v69
	v_add_f32_e32 v66, v66, v70
	v_add_f32_e32 v66, v71, v66
	v_add_f32_e32 v55, v55, v66
	ds_bpermute_b32 v66, v245, v55
	s_waitcnt lgkmcnt(0)
	v_add_f32_e32 v55, v55, v66
	ds_bpermute_b32 v66, v246, v55
	s_and_saveexec_b64 s[0:1], s[36:37]
	s_cbranch_execz .LBB0_855
	s_waitcnt lgkmcnt(0)
	v_add_f32_e32 v55, v55, v66
	ds_write_b32 v247, v55 offset:43008
.LBB0_855:
	s_or_b64 exec, exec, s[0:1]
	s_waitcnt lgkmcnt(0)
	v_or_b32_e32 v66, 16, v54
	v_ashrrev_i32_e32 v67, 31, v66
	v_lshlrev_b64 v[68:69], 11, v[66:67]
	v_lshl_add_u64 v[68:69], v[124:125], 0, v[68:69]
	s_waitcnt vmcnt(5)
	v_mov_b32_e32 v72, v158
	v_mov_b32_e32 v73, v159
	v_mov_b32_e32 v74, v160
	v_mov_b32_e32 v75, v161
	v_lshlrev_b32_e32 v70, 16, v72
	v_mul_f32_e32 v55, 0xbfb8aa3b, v70
	v_exp_f32_e32 v55, v55
	v_and_b32_e32 v71, 0xffff0000, v72
	s_waitcnt vmcnt(4)
	v_mov_b32_e32 v80, v162
	v_mov_b32_e32 v81, v163
	v_mov_b32_e32 v82, v164
	v_mov_b32_e32 v83, v165
	v_lshlrev_b32_e32 v68, 16, v80
	v_and_b32_e32 v69, 0xffff0000, v80
	v_add_f32_e32 v55, 1.0, v55
	v_rcp_f32_e32 v76, v55
	v_mul_f32_e32 v55, 0xbfb8aa3b, v71
	v_exp_f32_e32 v55, v55
	s_nop 0
	v_add_f32_e32 v55, 1.0, v55
	v_rcp_f32_e32 v77, v55
	s_nop 0
	v_pk_mul_f32 v[70:71], v[76:77], v[70:71]
	s_nop 0
	v_pk_mul_f32 v[36:37], v[36:37], v[70:71]
	v_lshlrev_b32_e32 v70, 16, v73
	v_mul_f32_e32 v55, 0xbfb8aa3b, v70
	v_exp_f32_e32 v55, v55
	v_and_b32_e32 v71, 0xffff0000, v73
	v_lshlrev_b32_e32 v76, 16, v74
	v_and_b32_e32 v77, 0xffff0000, v74
	v_add_f32_e32 v55, 1.0, v55
	v_rcp_f32_e32 v72, v55
	v_mul_f32_e32 v55, 0xbfb8aa3b, v71
	v_exp_f32_e32 v55, v55
	v_lshlrev_b32_e32 v74, 16, v75
	v_and_b32_e32 v75, 0xffff0000, v75
	v_add_f32_e32 v55, 1.0, v55
	v_rcp_f32_e32 v73, v55
	v_mul_f32_e32 v55, 0xbfb8aa3b, v76
	v_exp_f32_e32 v55, v55
	v_pk_mul_f32 v[70:71], v[72:73], v[70:71]
	s_nop 0
	v_pk_mul_f32 v[38:39], v[38:39], v[70:71]
	v_add_f32_e32 v55, 1.0, v55
	v_rcp_f32_e32 v78, v55
	v_mul_f32_e32 v55, 0xbfb8aa3b, v77
	v_exp_f32_e32 v55, v55
	v_pk_mul_f32 v[72:73], v[36:37], v[36:37]
	v_pk_mul_f32 v[70:71], v[38:39], v[38:39]
	v_add_f32_e32 v67, v72, v73
	v_add_f32_e32 v55, 1.0, v55
	v_rcp_f32_e32 v79, v55
	v_mul_f32_e32 v55, 0xbfb8aa3b, v74
	v_exp_f32_e32 v55, v55
	v_add_f32_e32 v67, v67, v70
	v_pk_mul_f32 v[76:77], v[78:79], v[76:77]
	v_add_f32_e32 v67, v71, v67
	v_add_f32_e32 v55, 1.0, v55
	v_pk_mul_f32 v[44:45], v[44:45], v[76:77]
	v_rcp_f32_e32 v76, v55
	v_mul_f32_e32 v55, 0xbfb8aa3b, v75
	v_exp_f32_e32 v55, v55
	s_nop 0
	v_add_f32_e32 v55, 1.0, v55
	v_rcp_f32_e32 v77, v55
	v_mul_f32_e32 v55, 0xbfb8aa3b, v68
	v_exp_f32_e32 v55, v55
	v_pk_mul_f32 v[74:75], v[76:77], v[74:75]
	s_nop 0
	v_pk_mul_f32 v[46:47], v[46:47], v[74:75]
	v_add_f32_e32 v55, 1.0, v55
	v_rcp_f32_e32 v78, v55
	v_mul_f32_e32 v55, 0xbfb8aa3b, v69
	v_exp_f32_e32 v55, v55
	v_pk_mul_f32 v[76:77], v[44:45], v[44:45]
	v_pk_mul_f32 v[74:75], v[46:47], v[46:47]
	v_add_f32_e32 v55, 1.0, v55
	v_rcp_f32_e32 v79, v55
	s_nop 0
	v_pk_mul_f32 v[68:69], v[78:79], v[68:69]
	s_nop 0
	v_pk_mul_f32 v[20:21], v[20:21], v[68:69]
	v_lshlrev_b32_e32 v68, 16, v81
	v_mul_f32_e32 v55, 0xbfb8aa3b, v68
	v_exp_f32_e32 v55, v55
	v_and_b32_e32 v69, 0xffff0000, v81
	v_pk_mul_f32 v[80:81], v[20:21], v[20:21]
	v_add_f32_e32 v55, 1.0, v55
	v_rcp_f32_e32 v78, v55
	v_mul_f32_e32 v55, 0xbfb8aa3b, v69
	v_exp_f32_e32 v55, v55
	s_nop 0
	v_add_f32_e32 v55, 1.0, v55
	v_rcp_f32_e32 v79, v55
	s_nop 0
	v_pk_mul_f32 v[68:69], v[78:79], v[68:69]
	s_nop 0
	v_pk_mul_f32 v[22:23], v[22:23], v[68:69]
	v_lshlrev_b32_e32 v68, 16, v82
	v_mul_f32_e32 v55, 0xbfb8aa3b, v68
	v_exp_f32_e32 v55, v55
	v_and_b32_e32 v69, 0xffff0000, v82
	v_pk_mul_f32 v[78:79], v[22:23], v[22:23]
	v_add_f32_e32 v55, 1.0, v55
	v_rcp_f32_e32 v84, v55
	v_mul_f32_e32 v55, 0xbfb8aa3b, v69
	v_exp_f32_e32 v55, v55
	s_nop 0
	v_add_f32_e32 v55, 1.0, v55
	v_rcp_f32_e32 v85, v55
	s_nop 0
	v_pk_mul_f32 v[68:69], v[84:85], v[68:69]
	s_nop 0
	v_pk_mul_f32 v[32:33], v[32:33], v[68:69]
	v_lshlrev_b32_e32 v68, 16, v83
	v_mul_f32_e32 v55, 0xbfb8aa3b, v68
	v_exp_f32_e32 v55, v55
	v_and_b32_e32 v69, 0xffff0000, v83
	v_add_f32_e32 v55, 1.0, v55
	v_rcp_f32_e32 v82, v55
	v_mul_f32_e32 v55, 0xbfb8aa3b, v69
	v_exp_f32_e32 v55, v55
	s_nop 0
	v_add_f32_e32 v55, 1.0, v55
	v_rcp_f32_e32 v83, v55
	v_add_f32_e32 v55, v76, v77
	v_add_f32_e32 v55, v55, v74
	v_add_f32_e32 v55, v75, v55
	v_pk_mul_f32 v[68:69], v[82:83], v[68:69]
	v_add_f32_e32 v55, v67, v55
	v_pk_mul_f32 v[68:69], v[34:35], v[68:69]
	v_pk_mul_f32 v[34:35], v[32:33], v[32:33]
	v_add_f32_e32 v67, v80, v81
	v_pk_mul_f32 v[82:83], v[68:69], v[68:69]
	v_add_f32_e32 v67, v67, v78
	v_add_f32_e32 v34, v34, v35
	v_add_f32_e32 v67, v79, v67
	v_add_f32_e32 v34, v34, v82
	v_add_f32_e32 v55, v55, v67
	v_add_f32_e32 v34, v83, v34
	v_add_f32_e32 v34, v55, v34
	ds_bpermute_b32 v35, v245, v34
	s_waitcnt lgkmcnt(0)
	v_add_f32_e32 v34, v34, v35
	ds_bpermute_b32 v35, v246, v34
	s_and_saveexec_b64 s[0:1], s[36:37]
	s_cbranch_execz .LBB0_857
	s_waitcnt lgkmcnt(0)
	v_add_f32_e32 v34, v34, v35
	ds_write_b32 v247, v34 offset:43072
.LBB0_857:
	s_or_b64 exec, exec, s[0:1]
	v_or_b32_e32 v34, 32, v54
	s_waitcnt lgkmcnt(0)
	v_ashrrev_i32_e32 v35, 31, v34
	v_lshlrev_b64 v[70:71], 11, v[34:35]
	v_lshl_add_u64 v[70:71], v[124:125], 0, v[70:71]
	s_waitcnt vmcnt(3)
	v_mov_b32_e32 v74, v166
	v_mov_b32_e32 v75, v167
	v_mov_b32_e32 v76, v168
	v_mov_b32_e32 v77, v169
	v_lshlrev_b32_e32 v72, 16, v74
	v_mul_f32_e32 v35, 0xbfb8aa3b, v72
	v_exp_f32_e32 v35, v35
	v_and_b32_e32 v73, 0xffff0000, v74
	s_waitcnt vmcnt(2)
	v_mov_b32_e32 v82, v170
	v_mov_b32_e32 v83, v171
	v_mov_b32_e32 v84, v172
	v_mov_b32_e32 v85, v173
	v_lshlrev_b32_e32 v70, 16, v82
	v_and_b32_e32 v71, 0xffff0000, v82
	v_add_f32_e32 v35, 1.0, v35
	v_rcp_f32_e32 v78, v35
	v_mul_f32_e32 v35, 0xbfb8aa3b, v73
	v_exp_f32_e32 v35, v35
	s_nop 0
	v_add_f32_e32 v35, 1.0, v35
	v_rcp_f32_e32 v79, v35
	s_nop 0
	v_pk_mul_f32 v[72:73], v[78:79], v[72:73]
	s_nop 0
	v_pk_mul_f32 v[8:9], v[8:9], v[72:73]
	v_lshlrev_b32_e32 v72, 16, v75
	v_mul_f32_e32 v35, 0xbfb8aa3b, v72
	v_exp_f32_e32 v35, v35
	v_and_b32_e32 v73, 0xffff0000, v75
	v_lshlrev_b32_e32 v78, 16, v76
	v_and_b32_e32 v79, 0xffff0000, v76
	v_add_f32_e32 v35, 1.0, v35
	v_rcp_f32_e32 v74, v35
	v_mul_f32_e32 v35, 0xbfb8aa3b, v73
	v_exp_f32_e32 v35, v35
	v_lshlrev_b32_e32 v76, 16, v77
	v_and_b32_e32 v77, 0xffff0000, v77
	v_add_f32_e32 v35, 1.0, v35
	v_rcp_f32_e32 v75, v35
	v_mul_f32_e32 v35, 0xbfb8aa3b, v78
	v_exp_f32_e32 v35, v35
	v_pk_mul_f32 v[72:73], v[74:75], v[72:73]
	s_nop 0
	v_pk_mul_f32 v[10:11], v[10:11], v[72:73]
	v_add_f32_e32 v35, 1.0, v35
	v_rcp_f32_e32 v80, v35
	v_mul_f32_e32 v35, 0xbfb8aa3b, v79
	v_exp_f32_e32 v35, v35
	v_pk_mul_f32 v[74:75], v[8:9], v[8:9]
	v_pk_mul_f32 v[72:73], v[10:11], v[10:11]
	v_add_f32_e32 v55, v74, v75
	v_add_f32_e32 v35, 1.0, v35
	v_rcp_f32_e32 v81, v35
	v_mul_f32_e32 v35, 0xbfb8aa3b, v76
	v_exp_f32_e32 v35, v35
	v_add_f32_e32 v55, v55, v72
	v_pk_mul_f32 v[78:79], v[80:81], v[78:79]
	v_add_f32_e32 v55, v73, v55
	v_add_f32_e32 v35, 1.0, v35
	v_pk_mul_f32 v[12:13], v[12:13], v[78:79]
	v_rcp_f32_e32 v78, v35
	v_mul_f32_e32 v35, 0xbfb8aa3b, v77
	v_exp_f32_e32 v35, v35
	s_nop 0
	v_add_f32_e32 v35, 1.0, v35
	v_rcp_f32_e32 v79, v35
	v_mul_f32_e32 v35, 0xbfb8aa3b, v70
	v_exp_f32_e32 v35, v35
	v_pk_mul_f32 v[76:77], v[78:79], v[76:77]
	s_nop 0
	v_pk_mul_f32 v[14:15], v[14:15], v[76:77]
	v_add_f32_e32 v35, 1.0, v35
	v_rcp_f32_e32 v80, v35
	v_mul_f32_e32 v35, 0xbfb8aa3b, v71
	v_exp_f32_e32 v35, v35
	v_pk_mul_f32 v[78:79], v[12:13], v[12:13]
	v_pk_mul_f32 v[76:77], v[14:15], v[14:15]
	v_add_f32_e32 v35, 1.0, v35
	v_rcp_f32_e32 v81, v35
	s_nop 0
	v_pk_mul_f32 v[70:71], v[80:81], v[70:71]
	s_nop 0
	v_pk_mul_f32 v[0:1], v[0:1], v[70:71]
	v_lshlrev_b32_e32 v70, 16, v83
	v_mul_f32_e32 v35, 0xbfb8aa3b, v70
	v_exp_f32_e32 v35, v35
	v_and_b32_e32 v71, 0xffff0000, v83
	v_pk_mul_f32 v[82:83], v[0:1], v[0:1]
	v_add_f32_e32 v35, 1.0, v35
	v_rcp_f32_e32 v80, v35
	v_mul_f32_e32 v35, 0xbfb8aa3b, v71
	v_exp_f32_e32 v35, v35
	s_nop 0
	v_add_f32_e32 v35, 1.0, v35
	v_rcp_f32_e32 v81, v35
	s_nop 0
	v_pk_mul_f32 v[70:71], v[80:81], v[70:71]
	s_nop 0
	v_pk_mul_f32 v[2:3], v[2:3], v[70:71]
	v_lshlrev_b32_e32 v70, 16, v84
	v_mul_f32_e32 v35, 0xbfb8aa3b, v70
	v_exp_f32_e32 v35, v35
	v_and_b32_e32 v71, 0xffff0000, v84
	v_pk_mul_f32 v[80:81], v[2:3], v[2:3]
	v_add_f32_e32 v35, 1.0, v35
	v_rcp_f32_e32 v86, v35
	v_mul_f32_e32 v35, 0xbfb8aa3b, v71
	v_exp_f32_e32 v35, v35
	s_nop 0
	v_add_f32_e32 v35, 1.0, v35
	v_rcp_f32_e32 v87, v35
	s_nop 0
	v_pk_mul_f32 v[70:71], v[86:87], v[70:71]
	s_nop 0
	v_pk_mul_f32 v[4:5], v[4:5], v[70:71]
	v_lshlrev_b32_e32 v70, 16, v85
	v_mul_f32_e32 v35, 0xbfb8aa3b, v70
	v_exp_f32_e32 v35, v35
	v_and_b32_e32 v71, 0xffff0000, v85
	v_add_f32_e32 v35, 1.0, v35
	v_rcp_f32_e32 v84, v35
	v_mul_f32_e32 v35, 0xbfb8aa3b, v71
	v_exp_f32_e32 v35, v35
	s_nop 0
	v_add_f32_e32 v35, 1.0, v35
	v_rcp_f32_e32 v85, v35
	v_add_f32_e32 v35, v78, v79
	v_add_f32_e32 v35, v35, v76
	v_add_f32_e32 v35, v77, v35
	v_pk_mul_f32 v[70:71], v[84:85], v[70:71]
	v_add_f32_e32 v35, v55, v35
	v_pk_mul_f32 v[70:71], v[6:7], v[70:71]
	v_pk_mul_f32 v[6:7], v[4:5], v[4:5]
	v_add_f32_e32 v55, v82, v83
	v_pk_mul_f32 v[84:85], v[70:71], v[70:71]
	v_add_f32_e32 v55, v55, v80
	v_add_f32_e32 v6, v6, v7
	v_add_f32_e32 v55, v81, v55
	v_add_f32_e32 v6, v6, v84
	v_add_f32_e32 v35, v35, v55
	v_add_f32_e32 v6, v85, v6
	v_add_f32_e32 v6, v35, v6
	ds_bpermute_b32 v7, v245, v6
	s_waitcnt lgkmcnt(0)
	v_add_f32_e32 v6, v6, v7
	ds_bpermute_b32 v7, v246, v6
	s_and_saveexec_b64 s[0:1], s[36:37]
	s_cbranch_execz .LBB0_859
	s_waitcnt lgkmcnt(0)
	v_add_f32_e32 v6, v6, v7
	ds_write_b32 v247, v6 offset:43136
.LBB0_859:
	s_or_b64 exec, exec, s[0:1]
	v_or_b32_e32 v72, 48, v54
	v_ashrrev_i32_e32 v73, 31, v72
	s_waitcnt lgkmcnt(0)
	v_lshlrev_b64 v[6:7], 11, v[72:73]
	v_lshl_add_u64 v[80:81], v[124:125], 0, v[6:7]
	s_waitcnt vmcnt(1)
	v_mov_b32_e32 v76, v174
	v_mov_b32_e32 v77, v175
	v_mov_b32_e32 v78, v176
	v_mov_b32_e32 v79, v177
	v_lshlrev_b32_e32 v6, 16, v76
	v_mul_f32_e32 v35, 0xbfb8aa3b, v6
	v_exp_f32_e32 v35, v35
	v_and_b32_e32 v7, 0xffff0000, v76
	v_add_f32_e32 v35, 1.0, v35
	v_rcp_f32_e32 v74, v35
	v_mul_f32_e32 v35, 0xbfb8aa3b, v7
	v_exp_f32_e32 v35, v35
	s_nop 0
	v_add_f32_e32 v35, 1.0, v35
	v_rcp_f32_e32 v75, v35
	s_nop 0
	v_pk_mul_f32 v[6:7], v[74:75], v[6:7]
	s_nop 0
	v_pk_mul_f32 v[6:7], v[28:29], v[6:7]
	v_lshlrev_b32_e32 v28, 16, v77
	v_mul_f32_e32 v35, 0xbfb8aa3b, v28
	v_exp_f32_e32 v35, v35
	v_and_b32_e32 v29, 0xffff0000, v77
	v_pk_mul_f32 v[76:77], v[6:7], v[6:7]
	v_add_f32_e32 v35, 1.0, v35
	v_rcp_f32_e32 v74, v35
	v_mul_f32_e32 v35, 0xbfb8aa3b, v29
	v_exp_f32_e32 v35, v35
	s_nop 0
	v_add_f32_e32 v35, 1.0, v35
	v_rcp_f32_e32 v75, v35
	s_nop 0
	v_pk_mul_f32 v[28:29], v[74:75], v[28:29]
	s_nop 0
	v_pk_mul_f32 v[28:29], v[30:31], v[28:29]
	v_lshlrev_b32_e32 v30, 16, v78
	v_mul_f32_e32 v35, 0xbfb8aa3b, v30
	v_exp_f32_e32 v35, v35
	v_and_b32_e32 v31, 0xffff0000, v78
	v_pk_mul_f32 v[74:75], v[28:29], v[28:29]
	v_add_f32_e32 v35, 1.0, v35
	v_rcp_f32_e32 v82, v35
	v_mul_f32_e32 v35, 0xbfb8aa3b, v31
	v_exp_f32_e32 v35, v35
	s_nop 0
	v_add_f32_e32 v35, 1.0, v35
	v_rcp_f32_e32 v83, v35
	s_nop 0
	v_pk_mul_f32 v[30:31], v[82:83], v[30:31]
	v_pk_mul_f32 v[30:31], v[40:41], v[30:31]
	v_lshlrev_b32_e32 v40, 16, v79
	v_mul_f32_e32 v35, 0xbfb8aa3b, v40
	v_exp_f32_e32 v35, v35
	v_and_b32_e32 v41, 0xffff0000, v79
	v_add_f32_e32 v35, 1.0, v35
	v_rcp_f32_e32 v78, v35
	v_mul_f32_e32 v35, 0xbfb8aa3b, v41
	v_exp_f32_e32 v35, v35
	s_waitcnt vmcnt(0)
	v_mov_b32_e32 v82, v178
	v_mov_b32_e32 v83, v179
	v_mov_b32_e32 v84, v180
	v_mov_b32_e32 v85, v181
	v_lshlrev_b32_e32 v80, 16, v82
	v_add_f32_e32 v35, 1.0, v35
	v_rcp_f32_e32 v79, v35
	v_mul_f32_e32 v35, 0xbfb8aa3b, v80
	v_exp_f32_e32 v35, v35
	v_and_b32_e32 v81, 0xffff0000, v82
	v_pk_mul_f32 v[40:41], v[78:79], v[40:41]
	v_pk_mul_f32 v[78:79], v[30:31], v[30:31]
	v_add_f32_e32 v35, 1.0, v35
	v_rcp_f32_e32 v86, v35
	v_mul_f32_e32 v35, 0xbfb8aa3b, v81
	v_exp_f32_e32 v35, v35
	v_pk_mul_f32 v[40:41], v[42:43], v[40:41]
	v_add_f32_e32 v35, 1.0, v35
	v_rcp_f32_e32 v87, v35
	v_pk_mul_f32 v[42:43], v[40:41], v[40:41]
	v_pk_mul_f32 v[80:81], v[86:87], v[80:81]
	s_nop 0
	v_pk_mul_f32 v[16:17], v[16:17], v[80:81]
	v_lshlrev_b32_e32 v80, 16, v83
	v_mul_f32_e32 v35, 0xbfb8aa3b, v80
	v_exp_f32_e32 v35, v35
	v_and_b32_e32 v81, 0xffff0000, v83
	v_lshlrev_b32_e32 v86, 16, v84
	v_and_b32_e32 v87, 0xffff0000, v84
	v_add_f32_e32 v35, 1.0, v35
	v_rcp_f32_e32 v82, v35
	v_mul_f32_e32 v35, 0xbfb8aa3b, v81
	v_exp_f32_e32 v35, v35
	v_lshlrev_b32_e32 v84, 16, v85
	v_and_b32_e32 v85, 0xffff0000, v85
	v_add_f32_e32 v35, 1.0, v35
	v_rcp_f32_e32 v83, v35
	v_mul_f32_e32 v35, 0xbfb8aa3b, v86
	v_exp_f32_e32 v35, v35
	v_pk_mul_f32 v[80:81], v[82:83], v[80:81]
	s_nop 0
	v_pk_mul_f32 v[18:19], v[18:19], v[80:81]
	v_add_f32_e32 v35, 1.0, v35
	v_rcp_f32_e32 v88, v35
	v_mul_f32_e32 v35, 0xbfb8aa3b, v87
	v_exp_f32_e32 v35, v35
	v_pk_mul_f32 v[82:83], v[16:17], v[16:17]
	v_pk_mul_f32 v[80:81], v[18:19], v[18:19]
	v_add_f32_e32 v35, 1.0, v35
	v_rcp_f32_e32 v89, v35
	v_mul_f32_e32 v35, 0xbfb8aa3b, v84
	v_exp_f32_e32 v35, v35
	v_pk_mul_f32 v[86:87], v[88:89], v[86:87]
	s_nop 0
	v_pk_mul_f32 v[24:25], v[24:25], v[86:87]
	v_add_f32_e32 v35, 1.0, v35
	v_rcp_f32_e32 v86, v35
	v_mul_f32_e32 v35, 0xbfb8aa3b, v85
	v_exp_f32_e32 v35, v35
	s_nop 0
	v_add_f32_e32 v35, 1.0, v35
	v_rcp_f32_e32 v87, v35
	v_add_f32_e32 v35, v78, v79
	v_add_f32_e32 v35, v35, v42
	v_add_f32_e32 v42, v76, v77
	v_add_f32_e32 v42, v42, v74
	v_add_f32_e32 v35, v43, v35
	v_add_f32_e32 v42, v75, v42
	v_add_f32_e32 v35, v42, v35
	v_add_f32_e32 v42, v82, v83
	v_pk_mul_f32 v[84:85], v[86:87], v[84:85]
	v_add_f32_e32 v42, v42, v80
	v_pk_mul_f32 v[26:27], v[26:27], v[84:85]
	v_pk_mul_f32 v[84:85], v[24:25], v[24:25]
	v_add_f32_e32 v42, v81, v42
	v_pk_mul_f32 v[86:87], v[26:27], v[26:27]
	v_add_f32_e32 v35, v35, v42
	v_add_f32_e32 v42, v84, v85
	v_add_f32_e32 v42, v42, v86
	v_add_f32_e32 v42, v87, v42
	v_add_f32_e32 v35, v35, v42
	ds_bpermute_b32 v42, v245, v35
	s_waitcnt lgkmcnt(0)
	v_add_f32_e32 v35, v35, v42
	ds_bpermute_b32 v42, v246, v35
	s_and_saveexec_b64 s[0:1], s[36:37]
	s_cbranch_execz .LBB0_848
	s_waitcnt lgkmcnt(0)
	v_add_f32_e32 v35, v35, v42
	ds_write_b32 v248, v35 offset:43008
	s_branch .LBB0_848
